# attention loop: ping-pong wave roles + deep LDS read pipelining + counted vmcnt; P1 adaLN row loop hand-rewritten with batched loads
# speedup vs baseline: 1.0297x; 1.0297x over previous
.LBB0_28:
	s_waitcnt vmcnt(21)
	v_lshlrev_b32_e32 v51, 16, v46
	v_and_b32_e32 v46, 0xffff0000, v46
	s_waitcnt vmcnt(6)
	v_mul_f32_e32 v51, v50, v51
	v_mul_f32_e32 v46, v50, v46
	v_cvt_pk_bf16_f32 v126, v51, v46
	v_lshlrev_b32_e32 v46, 16, v47
	v_and_b32_e32 v47, 0xffff0000, v47
	v_mul_f32_e32 v46, v50, v46
	v_mul_f32_e32 v47, v50, v47
	v_cvt_pk_bf16_f32 v127, v46, v47
	v_lshlrev_b32_e32 v46, 16, v48
	v_and_b32_e32 v47, 0xffff0000, v48
	v_mul_f32_e32 v46, v50, v46
	v_mul_f32_e32 v47, v50, v47
	v_cvt_pk_bf16_f32 v128, v46, v47
	v_lshlrev_b32_e32 v46, 16, v49
	v_and_b32_e32 v47, 0xffff0000, v49
	v_mul_f32_e32 v46, v50, v46
	v_mul_f32_e32 v47, v50, v47
	v_cvt_pk_bf16_f32 v129, v46, v47
	v_lshlrev_b32_e32 v46, 16, v42
	v_and_b32_e32 v42, 0xffff0000, v42
	v_mul_f32_e32 v46, v50, v46
	v_mul_f32_e32 v42, v50, v42
	v_cvt_pk_bf16_f32 v142, v46, v42
	v_lshlrev_b32_e32 v42, 16, v43
	v_and_b32_e32 v43, 0xffff0000, v43
	v_mul_f32_e32 v42, v50, v42
	v_mul_f32_e32 v43, v50, v43
	v_cvt_pk_bf16_f32 v143, v42, v43
	v_lshlrev_b32_e32 v42, 16, v44
	v_and_b32_e32 v43, 0xffff0000, v44
	v_mul_f32_e32 v42, v50, v42
	v_mul_f32_e32 v43, v50, v43
	v_cvt_pk_bf16_f32 v144, v42, v43
	v_lshlrev_b32_e32 v42, 16, v45
	v_and_b32_e32 v43, 0xffff0000, v45
	v_mul_f32_e32 v42, v50, v42
	v_mul_f32_e32 v43, v50, v43
	v_cvt_pk_bf16_f32 v145, v42, v43
	v_lshlrev_b32_e32 v42, 16, v38
	v_and_b32_e32 v38, 0xffff0000, v38
	v_mul_f32_e32 v42, v50, v42
	v_mul_f32_e32 v38, v50, v38
	v_cvt_pk_bf16_f32 v146, v42, v38
	v_lshlrev_b32_e32 v38, 16, v39
	v_and_b32_e32 v39, 0xffff0000, v39
	v_mul_f32_e32 v38, v50, v38
	v_mul_f32_e32 v39, v50, v39
	v_cvt_pk_bf16_f32 v147, v38, v39
	v_lshlrev_b32_e32 v38, 16, v40
	v_and_b32_e32 v39, 0xffff0000, v40
	v_mul_f32_e32 v38, v50, v38
	v_mul_f32_e32 v39, v50, v39
	v_cvt_pk_bf16_f32 v148, v38, v39
	v_lshlrev_b32_e32 v38, 16, v41
	v_and_b32_e32 v39, 0xffff0000, v41
	v_mul_f32_e32 v38, v50, v38
	v_mul_f32_e32 v39, v50, v39
	v_cvt_pk_bf16_f32 v149, v38, v39
	v_lshlrev_b32_e32 v38, 16, v34
	v_and_b32_e32 v34, 0xffff0000, v34
	v_mul_f32_e32 v38, v50, v38
	v_mul_f32_e32 v34, v50, v34
	v_cvt_pk_bf16_f32 v150, v38, v34
	v_lshlrev_b32_e32 v34, 16, v35
	v_and_b32_e32 v35, 0xffff0000, v35
	v_mul_f32_e32 v34, v50, v34
	v_mul_f32_e32 v35, v50, v35
	v_cvt_pk_bf16_f32 v151, v34, v35
	v_lshlrev_b32_e32 v34, 16, v36
	v_and_b32_e32 v35, 0xffff0000, v36
	v_mul_f32_e32 v34, v50, v34
	v_mul_f32_e32 v35, v50, v35
	v_cvt_pk_bf16_f32 v152, v34, v35
	v_lshlrev_b32_e32 v34, 16, v37
	v_and_b32_e32 v35, 0xffff0000, v37
	v_mul_f32_e32 v34, v50, v34
	v_mul_f32_e32 v35, v50, v35
	v_cvt_pk_bf16_f32 v153, v34, v35
	v_lshlrev_b32_e32 v34, 16, v30
	v_and_b32_e32 v30, 0xffff0000, v30
	v_mul_f32_e32 v34, v50, v34
	v_mul_f32_e32 v30, v50, v30
	v_cvt_pk_bf16_f32 v154, v34, v30
	v_lshlrev_b32_e32 v30, 16, v31
	v_and_b32_e32 v31, 0xffff0000, v31
	v_mul_f32_e32 v30, v50, v30
	v_mul_f32_e32 v31, v50, v31
	v_cvt_pk_bf16_f32 v155, v30, v31
	v_lshlrev_b32_e32 v30, 16, v32
	v_and_b32_e32 v31, 0xffff0000, v32
	v_mul_f32_e32 v30, v50, v30
	v_mul_f32_e32 v31, v50, v31
	v_cvt_pk_bf16_f32 v156, v30, v31
	v_lshlrev_b32_e32 v30, 16, v33
	v_and_b32_e32 v31, 0xffff0000, v33
	v_mul_f32_e32 v30, v50, v30
	v_mul_f32_e32 v31, v50, v31
	v_cvt_pk_bf16_f32 v157, v30, v31
	v_lshlrev_b32_e32 v30, 16, v26
	v_and_b32_e32 v26, 0xffff0000, v26
	v_mul_f32_e32 v30, v50, v30
	v_mul_f32_e32 v26, v50, v26
	v_cvt_pk_bf16_f32 v158, v30, v26
	v_lshlrev_b32_e32 v26, 16, v27
	v_and_b32_e32 v27, 0xffff0000, v27
	v_mul_f32_e32 v26, v50, v26
	v_mul_f32_e32 v27, v50, v27
	v_cvt_pk_bf16_f32 v159, v26, v27
	v_lshlrev_b32_e32 v26, 16, v28
	v_and_b32_e32 v27, 0xffff0000, v28
	v_mul_f32_e32 v26, v50, v26
	v_mul_f32_e32 v27, v50, v27
	v_cvt_pk_bf16_f32 v160, v26, v27
	v_lshlrev_b32_e32 v26, 16, v29
	v_and_b32_e32 v27, 0xffff0000, v29
	v_mul_f32_e32 v26, v50, v26
	v_mul_f32_e32 v27, v50, v27
	v_cvt_pk_bf16_f32 v161, v26, v27
	v_lshlrev_b32_e32 v26, 16, v22
	v_and_b32_e32 v22, 0xffff0000, v22
	v_mul_f32_e32 v26, v50, v26
	v_mul_f32_e32 v22, v50, v22
	v_cvt_pk_bf16_f32 v162, v26, v22
	v_lshlrev_b32_e32 v22, 16, v23
	v_and_b32_e32 v23, 0xffff0000, v23
	v_mul_f32_e32 v22, v50, v22
	v_mul_f32_e32 v23, v50, v23
	v_cvt_pk_bf16_f32 v163, v22, v23
	v_lshlrev_b32_e32 v22, 16, v24
	v_and_b32_e32 v23, 0xffff0000, v24
	v_mul_f32_e32 v22, v50, v22
	v_mul_f32_e32 v23, v50, v23
	v_cvt_pk_bf16_f32 v164, v22, v23
	v_lshlrev_b32_e32 v22, 16, v25
	v_and_b32_e32 v23, 0xffff0000, v25
	v_mul_f32_e32 v22, v50, v22
	v_mul_f32_e32 v23, v50, v23
	v_cvt_pk_bf16_f32 v165, v22, v23
	v_lshlrev_b32_e32 v22, 16, v18
	v_and_b32_e32 v18, 0xffff0000, v18
	v_mul_f32_e32 v22, v50, v22
	v_mul_f32_e32 v18, v50, v18
	v_cvt_pk_bf16_f32 v166, v22, v18
	v_lshlrev_b32_e32 v18, 16, v19
	v_and_b32_e32 v19, 0xffff0000, v19
	v_mul_f32_e32 v18, v50, v18
	v_mul_f32_e32 v19, v50, v19
	v_cvt_pk_bf16_f32 v167, v18, v19
	v_lshlrev_b32_e32 v18, 16, v20
	v_and_b32_e32 v19, 0xffff0000, v20
	v_mul_f32_e32 v18, v50, v18
	v_mul_f32_e32 v19, v50, v19
	v_cvt_pk_bf16_f32 v168, v18, v19
	v_lshlrev_b32_e32 v18, 16, v21
	v_and_b32_e32 v19, 0xffff0000, v21
	v_mul_f32_e32 v18, v50, v18
	v_mul_f32_e32 v19, v50, v19
	v_cvt_pk_bf16_f32 v169, v18, v19
	v_lshlrev_b32_e32 v18, 16, v14
	v_and_b32_e32 v14, 0xffff0000, v14
	v_mul_f32_e32 v18, v50, v18
	v_mul_f32_e32 v14, v50, v14
	v_cvt_pk_bf16_f32 v170, v18, v14
	v_lshlrev_b32_e32 v14, 16, v15
	v_and_b32_e32 v15, 0xffff0000, v15
	v_mul_f32_e32 v14, v50, v14
	v_mul_f32_e32 v15, v50, v15
	v_cvt_pk_bf16_f32 v171, v14, v15
	v_lshlrev_b32_e32 v14, 16, v16
	v_and_b32_e32 v15, 0xffff0000, v16
	v_mul_f32_e32 v14, v50, v14
	v_mul_f32_e32 v15, v50, v15
	v_cvt_pk_bf16_f32 v172, v14, v15
	v_lshlrev_b32_e32 v14, 16, v17
	v_and_b32_e32 v15, 0xffff0000, v17
	v_mul_f32_e32 v14, v50, v14
	v_mul_f32_e32 v15, v50, v15
	v_cvt_pk_bf16_f32 v173, v14, v15
	v_lshlrev_b32_e32 v14, 16, v10
	v_and_b32_e32 v10, 0xffff0000, v10
	v_mul_f32_e32 v14, v50, v14
	v_mul_f32_e32 v10, v50, v10
	v_cvt_pk_bf16_f32 v174, v14, v10
	v_lshlrev_b32_e32 v10, 16, v11
	v_and_b32_e32 v11, 0xffff0000, v11
	v_mul_f32_e32 v10, v50, v10
	v_mul_f32_e32 v11, v50, v11
	v_cvt_pk_bf16_f32 v175, v10, v11
	v_lshlrev_b32_e32 v10, 16, v12
	v_and_b32_e32 v11, 0xffff0000, v12
	v_mul_f32_e32 v10, v50, v10
	v_mul_f32_e32 v11, v50, v11
	v_cvt_pk_bf16_f32 v176, v10, v11
	v_lshlrev_b32_e32 v10, 16, v13
	v_and_b32_e32 v11, 0xffff0000, v13
	v_mul_f32_e32 v10, v50, v10
	v_mul_f32_e32 v11, v50, v11
	v_cvt_pk_bf16_f32 v177, v10, v11
	v_lshlrev_b32_e32 v10, 16, v6
	v_and_b32_e32 v6, 0xffff0000, v6
	v_mul_f32_e32 v10, v50, v10
	v_mul_f32_e32 v6, v50, v6
	v_cvt_pk_bf16_f32 v178, v10, v6
	v_lshlrev_b32_e32 v6, 16, v7
	v_and_b32_e32 v7, 0xffff0000, v7
	v_mul_f32_e32 v6, v50, v6
	v_mul_f32_e32 v7, v50, v7
	v_cvt_pk_bf16_f32 v179, v6, v7
	v_lshlrev_b32_e32 v6, 16, v8
	v_and_b32_e32 v7, 0xffff0000, v8
	v_mul_f32_e32 v6, v50, v6
	v_mul_f32_e32 v7, v50, v7
	v_cvt_pk_bf16_f32 v180, v6, v7
	v_lshlrev_b32_e32 v6, 16, v9
	v_and_b32_e32 v7, 0xffff0000, v9
	v_mul_f32_e32 v6, v50, v6
	v_mul_f32_e32 v7, v50, v7
	v_cvt_pk_bf16_f32 v181, v6, v7
	v_lshlrev_b32_e32 v6, 16, v2
	v_and_b32_e32 v2, 0xffff0000, v2
	v_mul_f32_e32 v6, v50, v6
	v_mul_f32_e32 v2, v50, v2
	v_cvt_pk_bf16_f32 v182, v6, v2
	v_lshlrev_b32_e32 v2, 16, v3
	v_and_b32_e32 v3, 0xffff0000, v3
	v_mul_f32_e32 v2, v50, v2
	v_mul_f32_e32 v3, v50, v3
	v_cvt_pk_bf16_f32 v183, v2, v3
	v_lshlrev_b32_e32 v2, 16, v4
	v_and_b32_e32 v3, 0xffff0000, v4
	v_mul_f32_e32 v2, v50, v2
	v_mul_f32_e32 v3, v50, v3
	v_cvt_pk_bf16_f32 v184, v2, v3
	v_lshlrev_b32_e32 v2, 16, v5
	v_and_b32_e32 v3, 0xffff0000, v5
	v_mul_f32_e32 v2, v50, v2
	v_mul_f32_e32 v3, v50, v3
	v_cvt_pk_bf16_f32 v185, v2, v3
	v_lshl_add_u64 v[2:3], s[20:21], 0, v[198:199]
	s_mov_b64 s[14:15], 0x1c000
	v_lshl_add_u64 v[206:207], v[2:3], 0, s[14:15]
	v_mov_b64_e32 v[2:3], s[42:43]
	v_mov_b32_e32 v16, v1
	v_mov_b32_e32 v17, v1
	v_mad_i64_i32 v[208:209], s[14:15], v200, s11, v[2:3]
	v_mov_b32_e32 v2, v1
	v_mov_b32_e32 v3, v1
	v_mov_b32_e32 v4, v1
	v_mov_b32_e32 v5, v1
	v_mov_b32_e32 v6, v1
	v_mov_b32_e32 v7, v1
	v_mov_b32_e32 v8, v1
	v_mov_b32_e32 v9, v1
	v_mov_b32_e32 v10, v1
	v_mov_b32_e32 v11, v1
	v_mov_b32_e32 v12, v1
	v_mov_b32_e32 v13, v1
	v_mov_b32_e32 v14, v1
	v_mov_b32_e32 v15, v1
	v_mov_b64_e32 v[32:33], v[16:17]
	v_mov_b64_e32 v[48:49], v[16:17]
	v_mov_b64_e32 v[64:65], v[16:17]
	s_lshr_b32 s5, s11, 6
	v_mov_b32_e32 v224, 0
	v_mov_b32_e32 v223, 0xf149f2ca
	s_mov_b32 s11, 4
	v_mov_b64_e32 v[30:31], v[14:15]
	v_mov_b64_e32 v[28:29], v[12:13]
	v_mov_b64_e32 v[26:27], v[10:11]
	v_mov_b64_e32 v[24:25], v[8:9]
	v_mov_b64_e32 v[22:23], v[6:7]
	v_mov_b64_e32 v[20:21], v[4:5]
	v_mov_b64_e32 v[18:19], v[2:3]
	v_mov_b64_e32 v[46:47], v[14:15]
	v_mov_b64_e32 v[44:45], v[12:13]
	v_mov_b64_e32 v[42:43], v[10:11]
	v_mov_b64_e32 v[40:41], v[8:9]
	v_mov_b64_e32 v[38:39], v[6:7]
	v_mov_b64_e32 v[36:37], v[4:5]
	v_mov_b64_e32 v[34:35], v[2:3]
	v_mov_b64_e32 v[62:63], v[14:15]
	v_mov_b64_e32 v[60:61], v[12:13]
	v_mov_b64_e32 v[58:59], v[10:11]
	v_mov_b64_e32 v[56:57], v[8:9]
	v_mov_b64_e32 v[54:55], v[6:7]
	v_mov_b64_e32 v[52:53], v[4:5]
	v_mov_b64_e32 v[50:51], v[2:3]
	v_readlane_b32 s33, v254, 35
	s_mov_b32 s34, 0x18000
	s_waitcnt vmcnt(5)
	v_lshl_add_u64 v[204:205], v[204:205], 0, v[194:195]
	v_lshl_add_u64 v[208:209], v[208:209], 0, v[194:195]
	s_andn2_b64 vcc, exec, s[38:39]
	s_cbranch_vccnz .Latt2_A_loop
	s_branch .Latt2_B_pro
.Latt2_A_loop:
	ds_read_b128 v[226:229], v215
	ds_read_b128 v[236:239], v215 offset:12800
	ds_read_b128 v[240:243], v215 offset:32
	ds_read_b128 v[244:247], v215 offset:12832
	ds_read_b128 v[248:251], v215 offset:64
	ds_read_b128 v[210:213], v215 offset:12864
	s_waitcnt lgkmcnt(5)
	v_mfma_f32_32x32x16_bf16 v[82:97], v[226:229], v[126:129], 0
	ds_read_b128 v[226:229], v215 offset:96
	s_waitcnt lgkmcnt(5)
	v_mfma_f32_32x32x16_bf16 v[66:81], v[236:239], v[126:129], 0
	ds_read_b128 v[236:239], v215 offset:12896
	s_waitcnt lgkmcnt(5)
	v_mfma_f32_32x32x16_bf16 v[82:97], v[240:243], v[142:145], v[82:97]
	ds_read_b128 v[240:243], v215 offset:128
	s_waitcnt lgkmcnt(5)
	v_mfma_f32_32x32x16_bf16 v[66:81], v[244:247], v[142:145], v[66:81]
	ds_read_b128 v[244:247], v215 offset:12928
	s_waitcnt lgkmcnt(5)
	v_mfma_f32_32x32x16_bf16 v[82:97], v[248:251], v[146:149], v[82:97]
	ds_read_b128 v[248:251], v215 offset:160
	s_waitcnt lgkmcnt(5)
	v_mfma_f32_32x32x16_bf16 v[66:81], v[210:213], v[146:149], v[66:81]
	ds_read_b128 v[210:213], v215 offset:12960
	s_waitcnt lgkmcnt(5)
	v_mfma_f32_32x32x16_bf16 v[82:97], v[226:229], v[150:153], v[82:97]
	ds_read_b128 v[226:229], v215 offset:192
	s_waitcnt lgkmcnt(5)
	v_mfma_f32_32x32x16_bf16 v[66:81], v[236:239], v[150:153], v[66:81]
	ds_read_b128 v[236:239], v215 offset:12992
	s_waitcnt lgkmcnt(5)
	v_mfma_f32_32x32x16_bf16 v[82:97], v[240:243], v[154:157], v[82:97]
	ds_read_b128 v[240:243], v215 offset:224
	s_waitcnt lgkmcnt(5)
	v_mfma_f32_32x32x16_bf16 v[66:81], v[244:247], v[154:157], v[66:81]
	ds_read_b128 v[244:247], v215 offset:13024
	s_waitcnt lgkmcnt(5)
	v_mfma_f32_32x32x16_bf16 v[82:97], v[248:251], v[158:161], v[82:97]
	ds_read_b128 v[248:251], v215 offset:256
	s_waitcnt lgkmcnt(5)
	v_mfma_f32_32x32x16_bf16 v[66:81], v[210:213], v[158:161], v[66:81]
	ds_read_b128 v[210:213], v215 offset:13056
	s_waitcnt lgkmcnt(5)
	v_mfma_f32_32x32x16_bf16 v[82:97], v[226:229], v[162:165], v[82:97]
	ds_read_b128 v[226:229], v215 offset:288
	s_waitcnt lgkmcnt(5)
	v_mfma_f32_32x32x16_bf16 v[66:81], v[236:239], v[162:165], v[66:81]
	ds_read_b128 v[236:239], v215 offset:13088
	s_waitcnt lgkmcnt(5)
	v_mfma_f32_32x32x16_bf16 v[82:97], v[240:243], v[166:169], v[82:97]
	ds_read_b128 v[240:243], v215 offset:320
	s_waitcnt lgkmcnt(5)
	v_mfma_f32_32x32x16_bf16 v[66:81], v[244:247], v[166:169], v[66:81]
	ds_read_b128 v[244:247], v215 offset:13120
	s_waitcnt lgkmcnt(5)
	v_mfma_f32_32x32x16_bf16 v[82:97], v[248:251], v[170:173], v[82:97]
	ds_read_b128 v[248:251], v215 offset:352
	s_waitcnt lgkmcnt(5)
	v_mfma_f32_32x32x16_bf16 v[66:81], v[210:213], v[170:173], v[66:81]
	ds_read_b128 v[210:213], v215 offset:13152
	s_waitcnt lgkmcnt(5)
	v_mfma_f32_32x32x16_bf16 v[82:97], v[226:229], v[174:177], v[82:97]
	s_waitcnt lgkmcnt(4)
	v_mfma_f32_32x32x16_bf16 v[66:81], v[236:239], v[174:177], v[66:81]
	s_waitcnt lgkmcnt(3)
	v_mfma_f32_32x32x16_bf16 v[82:97], v[240:243], v[178:181], v[82:97]
	s_waitcnt lgkmcnt(2)
	v_mfma_f32_32x32x16_bf16 v[66:81], v[244:247], v[178:181], v[66:81]
	s_waitcnt lgkmcnt(1)
	v_mfma_f32_32x32x16_bf16 v[82:97], v[248:251], v[182:185], v[82:97]
	s_waitcnt lgkmcnt(0)
	s_barrier
	v_mfma_f32_32x32x16_bf16 v[66:81], v[210:213], v[182:185], v[66:81]
	s_add_i32 s13, s11, -1
	s_cmp_ge_u32 s13, s5
	s_cbranch_scc1 .Latt2_wt_1
	s_waitcnt vmcnt(9)
	ds_write_b128 v219, v[102:105] offset:44032
	s_waitcnt vmcnt(8)
	ds_write_b128 v220, v[106:109] offset:44032
	s_waitcnt vmcnt(7)
	ds_write_b128 v221, v[114:117] offset:44032
	s_waitcnt vmcnt(6)
	ds_write_b128 v201, v[98:101]
	s_waitcnt vmcnt(5)
	ds_write_b128 v201, v[110:113] offset:9216
	v_add_co_u32_e32 v186, vcc, 0xffff6000, v206
	s_nop 1
	v_addc_co_u32_e32 v187, vcc, -1, v207, vcc
	global_load_dwordx4 v[102:105], v[186:187], off
	v_add_co_u32_e32 v186, vcc, 0xffff8000, v206
	s_nop 1
	v_addc_co_u32_e32 v187, vcc, -1, v207, vcc
	global_load_dwordx4 v[106:109], v[186:187], off
	v_add_co_u32_e32 v186, vcc, 0xffffa000, v206
	s_nop 1
	v_addc_co_u32_e32 v187, vcc, -1, v207, vcc
	global_load_dwordx4 v[114:117], v[186:187], off
	global_load_dwordx4 v[98:101], v[204:205], off offset:384
	global_load_dwordx4 v[110:113], v[208:209], off offset:384
	s_branch .Latt2_wd_2
.Latt2_wt_1:
	s_waitcnt vmcnt(4)
	ds_write_b128 v219, v[102:105] offset:44032
	s_waitcnt vmcnt(3)
	ds_write_b128 v220, v[106:109] offset:44032
	s_waitcnt vmcnt(2)
	ds_write_b128 v221, v[114:117] offset:44032
	s_waitcnt vmcnt(1)
	ds_write_b128 v201, v[98:101]
	s_waitcnt vmcnt(0)
	ds_write_b128 v201, v[110:113] offset:9216
.Latt2_wd_2:
	ds_read_b128 v[236:239], v216 offset:25600
	ds_read_b128 v[240:243], v216 offset:30208
	ds_read_b128 v[244:247], v216 offset:34816
	ds_read_b128 v[248:251], v216 offset:39424
	ds_read_b128 v[210:213], v216 offset:25632
	s_nop 4
	v_max_f32_e32 v186, v83, v83
	v_max_f32_e32 v187, v82, v82
	v_max_f32_e32 v186, v187, v186
	v_max3_f32 v186, v186, v84, v85
	v_max3_f32 v186, v186, v86, v87
	v_max3_f32 v186, v186, v88, v89
	v_max3_f32 v186, v186, v90, v91
	v_max3_f32 v186, v186, v92, v93
	v_max3_f32 v186, v186, v94, v95
	v_max3_f32 v186, v186, v96, v97
	v_max3_f32 v186, v186, v66, v67
	v_max3_f32 v186, v186, v68, v69
	v_max3_f32 v186, v186, v70, v71
	v_max3_f32 v186, v186, v72, v73
	v_max3_f32 v186, v186, v74, v75
	v_max3_f32 v186, v186, v76, v77
	v_max3_f32 v186, v186, v78, v79
	v_max3_f32 v186, v186, v80, v81
	ds_bpermute_b32 v187, v214, v186
	s_waitcnt lgkmcnt(0)
	v_max_f32_e32 v187, v187, v187
	v_max_f32_e32 v187, v186, v187
	v_add_f32_e32 v186, 0x41380000, v223
	v_cmp_gt_f32_e32 vcc, v187, v186
	s_cbranch_vccz .Latt2_nr_3
	v_max_f32_e32 v186, v187, v187
	v_max_f32_e32 v187, v223, v223
	v_max_f32_e32 v187, v187, v186
	v_sub_f32_e32 v186, v223, v187
	v_exp_f32_e32 v186, v186
	v_mov_b32_e32 v223, v187
	v_pk_mul_f32 v[64:65], v[64:65], v[186:187] op_sel_hi:[1,0]
	v_pk_mul_f32 v[62:63], v[62:63], v[186:187] op_sel_hi:[1,0]
	v_pk_mul_f32 v[60:61], v[60:61], v[186:187] op_sel_hi:[1,0]
	v_pk_mul_f32 v[58:59], v[58:59], v[186:187] op_sel_hi:[1,0]
	v_pk_mul_f32 v[56:57], v[56:57], v[186:187] op_sel_hi:[1,0]
	v_pk_mul_f32 v[54:55], v[54:55], v[186:187] op_sel_hi:[1,0]
	v_pk_mul_f32 v[52:53], v[52:53], v[186:187] op_sel_hi:[1,0]
	v_pk_mul_f32 v[50:51], v[50:51], v[186:187] op_sel_hi:[1,0]
	v_pk_mul_f32 v[48:49], v[48:49], v[186:187] op_sel_hi:[1,0]
	v_pk_mul_f32 v[46:47], v[46:47], v[186:187] op_sel_hi:[1,0]
	v_pk_mul_f32 v[44:45], v[44:45], v[186:187] op_sel_hi:[1,0]
	v_pk_mul_f32 v[42:43], v[42:43], v[186:187] op_sel_hi:[1,0]
	v_pk_mul_f32 v[40:41], v[40:41], v[186:187] op_sel_hi:[1,0]
	v_pk_mul_f32 v[38:39], v[38:39], v[186:187] op_sel_hi:[1,0]
	v_pk_mul_f32 v[36:37], v[36:37], v[186:187] op_sel_hi:[1,0]
	v_pk_mul_f32 v[34:35], v[34:35], v[186:187] op_sel_hi:[1,0]
	v_pk_mul_f32 v[32:33], v[32:33], v[186:187] op_sel_hi:[1,0]
	v_pk_mul_f32 v[30:31], v[30:31], v[186:187] op_sel_hi:[1,0]
	v_pk_mul_f32 v[28:29], v[28:29], v[186:187] op_sel_hi:[1,0]
	v_pk_mul_f32 v[26:27], v[26:27], v[186:187] op_sel_hi:[1,0]
	v_pk_mul_f32 v[24:25], v[24:25], v[186:187] op_sel_hi:[1,0]
	v_pk_mul_f32 v[22:23], v[22:23], v[186:187] op_sel_hi:[1,0]
	v_pk_mul_f32 v[20:21], v[20:21], v[186:187] op_sel_hi:[1,0]
	v_pk_mul_f32 v[18:19], v[18:19], v[186:187] op_sel_hi:[1,0]
	v_pk_mul_f32 v[16:17], v[16:17], v[186:187] op_sel_hi:[1,0]
	v_pk_mul_f32 v[14:15], v[14:15], v[186:187] op_sel_hi:[1,0]
	v_pk_mul_f32 v[12:13], v[12:13], v[186:187] op_sel_hi:[1,0]
	v_pk_mul_f32 v[10:11], v[10:11], v[186:187] op_sel_hi:[1,0]
	v_pk_mul_f32 v[8:9], v[8:9], v[186:187] op_sel_hi:[1,0]
	v_pk_mul_f32 v[6:7], v[6:7], v[186:187] op_sel_hi:[1,0]
	v_pk_mul_f32 v[4:5], v[4:5], v[186:187] op_sel_hi:[1,0]
	v_pk_mul_f32 v[2:3], v[2:3], v[186:187] op_sel_hi:[1,0]
	v_mul_f32_e32 v224, v224, v186
.Latt2_nr_3:
	v_sub_f32_e32 v82, v82, v223
	v_sub_f32_e32 v83, v83, v223
	v_sub_f32_e32 v84, v84, v223
	v_sub_f32_e32 v85, v85, v223
	v_exp_f32_e32 v82, v82
	v_exp_f32_e32 v83, v83
	v_exp_f32_e32 v84, v84
	v_exp_f32_e32 v85, v85
	v_sub_f32_e32 v86, v86, v223
	v_sub_f32_e32 v87, v87, v223
	v_sub_f32_e32 v88, v88, v223
	v_sub_f32_e32 v89, v89, v223
	v_exp_f32_e32 v86, v86
	v_exp_f32_e32 v87, v87
	v_exp_f32_e32 v88, v88
	v_exp_f32_e32 v89, v89
	v_cvt_pk_bf16_f32 v226, v82, v83
	v_cvt_pk_bf16_f32 v227, v84, v85
	v_cvt_pk_bf16_f32 v228, v86, v87
	v_cvt_pk_bf16_f32 v229, v88, v89
	s_nop 1
	v_mfma_f32_32x32x16_bf16 v[50:65], v[236:239], v[226:229], v[50:65]
	ds_read_b128 v[236:239], v216 offset:30240
	v_sub_f32_e32 v90, v90, v223
	v_sub_f32_e32 v91, v91, v223
	v_sub_f32_e32 v92, v92, v223
	v_sub_f32_e32 v93, v93, v223
	v_exp_f32_e32 v90, v90
	v_exp_f32_e32 v91, v91
	v_mfma_f32_32x32x16_bf16 v[34:49], v[240:243], v[226:229], v[34:49]
	ds_read_b128 v[240:243], v216 offset:34848
	v_exp_f32_e32 v92, v92
	v_exp_f32_e32 v93, v93
	v_sub_f32_e32 v94, v94, v223
	v_sub_f32_e32 v95, v95, v223
	v_sub_f32_e32 v96, v96, v223
	v_sub_f32_e32 v97, v97, v223
	v_mfma_f32_32x32x16_bf16 v[18:33], v[244:247], v[226:229], v[18:33]
	ds_read_b128 v[244:247], v216 offset:39456
	v_exp_f32_e32 v94, v94
	v_exp_f32_e32 v95, v95
	v_exp_f32_e32 v96, v96
	v_exp_f32_e32 v97, v97
	v_add_f32_e32 v186, 0, v82
	v_add_f32_e32 v186, v83, v186
	v_mfma_f32_32x32x16_bf16 v[2:17], v[248:251], v[226:229], v[2:17]
	ds_read_b128 v[248:251], v216 offset:25664
	v_add_f32_e32 v186, v84, v186
	v_add_f32_e32 v186, v85, v186
	v_add_f32_e32 v186, v86, v186
	v_add_f32_e32 v186, v87, v186
	v_add_f32_e32 v186, v88, v186
	v_add_f32_e32 v186, v89, v186
	v_cvt_pk_bf16_f32 v226, v90, v91
	v_cvt_pk_bf16_f32 v227, v92, v93
	v_cvt_pk_bf16_f32 v228, v94, v95
	v_cvt_pk_bf16_f32 v229, v96, v97
	s_nop 1
	v_mfma_f32_32x32x16_bf16 v[50:65], v[210:213], v[226:229], v[50:65]
	ds_read_b128 v[210:213], v216 offset:30272
	v_sub_f32_e32 v66, v66, v223
	v_sub_f32_e32 v67, v67, v223
	v_sub_f32_e32 v68, v68, v223
	v_sub_f32_e32 v69, v69, v223
	v_exp_f32_e32 v66, v66
	v_exp_f32_e32 v67, v67
	s_waitcnt lgkmcnt(4)
	v_mfma_f32_32x32x16_bf16 v[34:49], v[236:239], v[226:229], v[34:49]
	ds_read_b128 v[236:239], v216 offset:34880
	v_exp_f32_e32 v68, v68
	v_exp_f32_e32 v69, v69
	v_sub_f32_e32 v70, v70, v223
	v_sub_f32_e32 v71, v71, v223
	v_sub_f32_e32 v72, v72, v223
	v_sub_f32_e32 v73, v73, v223
	s_waitcnt lgkmcnt(4)
	v_mfma_f32_32x32x16_bf16 v[18:33], v[240:243], v[226:229], v[18:33]
	ds_read_b128 v[240:243], v216 offset:39488
	v_exp_f32_e32 v70, v70
	v_exp_f32_e32 v71, v71
	v_exp_f32_e32 v72, v72
	v_exp_f32_e32 v73, v73
	v_add_f32_e32 v186, v90, v186
	v_add_f32_e32 v186, v91, v186
	s_waitcnt lgkmcnt(4)
	v_mfma_f32_32x32x16_bf16 v[2:17], v[244:247], v[226:229], v[2:17]
	ds_read_b128 v[244:247], v216 offset:25696
	v_add_f32_e32 v186, v92, v186
	v_add_f32_e32 v186, v93, v186
	v_add_f32_e32 v186, v94, v186
	v_add_f32_e32 v186, v95, v186
	v_add_f32_e32 v186, v96, v186
	v_add_f32_e32 v186, v97, v186
	v_cvt_pk_bf16_f32 v226, v66, v67
	v_cvt_pk_bf16_f32 v227, v68, v69
	v_cvt_pk_bf16_f32 v228, v70, v71
	v_cvt_pk_bf16_f32 v229, v72, v73
	s_nop 1
	s_waitcnt lgkmcnt(4)
	v_mfma_f32_32x32x16_bf16 v[50:65], v[248:251], v[226:229], v[50:65]
	ds_read_b128 v[248:251], v216 offset:30304
	v_sub_f32_e32 v74, v74, v223
	v_sub_f32_e32 v75, v75, v223
	v_sub_f32_e32 v76, v76, v223
	v_sub_f32_e32 v77, v77, v223
	v_exp_f32_e32 v74, v74
	v_exp_f32_e32 v75, v75
	s_waitcnt lgkmcnt(4)
	v_mfma_f32_32x32x16_bf16 v[34:49], v[210:213], v[226:229], v[34:49]
	ds_read_b128 v[210:213], v216 offset:34912
	v_exp_f32_e32 v76, v76
	v_exp_f32_e32 v77, v77
	v_sub_f32_e32 v78, v78, v223
	v_sub_f32_e32 v79, v79, v223
	v_sub_f32_e32 v80, v80, v223
	v_sub_f32_e32 v81, v81, v223
	s_waitcnt lgkmcnt(4)
	v_mfma_f32_32x32x16_bf16 v[18:33], v[236:239], v[226:229], v[18:33]
	ds_read_b128 v[236:239], v216 offset:39520
	v_exp_f32_e32 v78, v78
	v_exp_f32_e32 v79, v79
	v_exp_f32_e32 v80, v80
	v_exp_f32_e32 v81, v81
	v_add_f32_e32 v186, v66, v186
	v_add_f32_e32 v186, v67, v186
	s_waitcnt lgkmcnt(4)
	v_mfma_f32_32x32x16_bf16 v[2:17], v[240:243], v[226:229], v[2:17]
	v_add_f32_e32 v186, v68, v186
	v_add_f32_e32 v186, v69, v186
	v_add_f32_e32 v186, v70, v186
	v_add_f32_e32 v186, v71, v186
	v_add_f32_e32 v186, v72, v186
	v_add_f32_e32 v186, v73, v186
	v_cvt_pk_bf16_f32 v226, v74, v75
	v_cvt_pk_bf16_f32 v227, v76, v77
	v_cvt_pk_bf16_f32 v228, v78, v79
	v_cvt_pk_bf16_f32 v229, v80, v81
	s_nop 1
	s_waitcnt lgkmcnt(3)
	v_mfma_f32_32x32x16_bf16 v[50:65], v[244:247], v[226:229], v[50:65]
	v_add_f32_e32 v186, v74, v186
	v_add_f32_e32 v186, v75, v186
	s_waitcnt lgkmcnt(2)
	v_mfma_f32_32x32x16_bf16 v[34:49], v[248:251], v[226:229], v[34:49]
	v_add_f32_e32 v186, v76, v186
	v_add_f32_e32 v186, v77, v186
	s_waitcnt lgkmcnt(1)
	v_mfma_f32_32x32x16_bf16 v[18:33], v[210:213], v[226:229], v[18:33]
	v_add_f32_e32 v186, v78, v186
	v_add_f32_e32 v186, v79, v186
	s_waitcnt lgkmcnt(0)
	s_barrier
	v_mfma_f32_32x32x16_bf16 v[2:17], v[236:239], v[226:229], v[2:17]
	v_add_f32_e32 v186, v80, v186
	v_add_f32_e32 v186, v81, v186
	v_add_f32_e32 v225, v224, v186
	ds_read_b128 v[226:229], v215 offset:44032
	ds_read_b128 v[236:239], v215 offset:56832
	ds_read_b128 v[240:243], v215 offset:44064
	ds_read_b128 v[244:247], v215 offset:56864
	ds_read_b128 v[248:251], v215 offset:44096
	ds_read_b128 v[210:213], v215 offset:56896
	s_waitcnt lgkmcnt(5)
	v_mfma_f32_32x32x16_bf16 v[82:97], v[226:229], v[126:129], 0
	ds_read_b128 v[226:229], v215 offset:44128
	s_waitcnt lgkmcnt(5)
	v_mfma_f32_32x32x16_bf16 v[66:81], v[236:239], v[126:129], 0
	ds_read_b128 v[236:239], v215 offset:56928
	s_waitcnt lgkmcnt(5)
	v_mfma_f32_32x32x16_bf16 v[82:97], v[240:243], v[142:145], v[82:97]
	ds_read_b128 v[240:243], v215 offset:44160
	s_waitcnt lgkmcnt(5)
	v_mfma_f32_32x32x16_bf16 v[66:81], v[244:247], v[142:145], v[66:81]
	ds_read_b128 v[244:247], v215 offset:56960
	s_waitcnt lgkmcnt(5)
	v_mfma_f32_32x32x16_bf16 v[82:97], v[248:251], v[146:149], v[82:97]
	ds_read_b128 v[248:251], v215 offset:44192
	s_waitcnt lgkmcnt(5)
	v_mfma_f32_32x32x16_bf16 v[66:81], v[210:213], v[146:149], v[66:81]
	ds_read_b128 v[210:213], v215 offset:56992
	s_waitcnt lgkmcnt(5)
	v_mfma_f32_32x32x16_bf16 v[82:97], v[226:229], v[150:153], v[82:97]
	ds_read_b128 v[226:229], v215 offset:44224
	s_waitcnt lgkmcnt(5)
	v_mfma_f32_32x32x16_bf16 v[66:81], v[236:239], v[150:153], v[66:81]
	ds_read_b128 v[236:239], v215 offset:57024
	s_waitcnt lgkmcnt(5)
	v_mfma_f32_32x32x16_bf16 v[82:97], v[240:243], v[154:157], v[82:97]
	ds_read_b128 v[240:243], v215 offset:44256
	s_waitcnt lgkmcnt(5)
	v_mfma_f32_32x32x16_bf16 v[66:81], v[244:247], v[154:157], v[66:81]
	ds_read_b128 v[244:247], v215 offset:57056
	s_waitcnt lgkmcnt(5)
	v_mfma_f32_32x32x16_bf16 v[82:97], v[248:251], v[158:161], v[82:97]
	ds_read_b128 v[248:251], v215 offset:44288
	s_waitcnt lgkmcnt(5)
	v_mfma_f32_32x32x16_bf16 v[66:81], v[210:213], v[158:161], v[66:81]
	ds_read_b128 v[210:213], v215 offset:57088
	s_waitcnt lgkmcnt(5)
	v_mfma_f32_32x32x16_bf16 v[82:97], v[226:229], v[162:165], v[82:97]
	ds_read_b128 v[226:229], v215 offset:44320
	s_waitcnt lgkmcnt(5)
	v_mfma_f32_32x32x16_bf16 v[66:81], v[236:239], v[162:165], v[66:81]
	ds_read_b128 v[236:239], v215 offset:57120
	s_waitcnt lgkmcnt(5)
	v_mfma_f32_32x32x16_bf16 v[82:97], v[240:243], v[166:169], v[82:97]
	ds_read_b128 v[240:243], v215 offset:44352
	s_waitcnt lgkmcnt(5)
	v_mfma_f32_32x32x16_bf16 v[66:81], v[244:247], v[166:169], v[66:81]
	ds_read_b128 v[244:247], v215 offset:57152
	s_waitcnt lgkmcnt(5)
	v_mfma_f32_32x32x16_bf16 v[82:97], v[248:251], v[170:173], v[82:97]
	ds_read_b128 v[248:251], v215 offset:44384
	s_waitcnt lgkmcnt(5)
	v_mfma_f32_32x32x16_bf16 v[66:81], v[210:213], v[170:173], v[66:81]
	ds_read_b128 v[210:213], v215 offset:57184
	s_waitcnt lgkmcnt(5)
	v_mfma_f32_32x32x16_bf16 v[82:97], v[226:229], v[174:177], v[82:97]
	s_waitcnt lgkmcnt(4)
	v_mfma_f32_32x32x16_bf16 v[66:81], v[236:239], v[174:177], v[66:81]
	s_waitcnt lgkmcnt(3)
	v_mfma_f32_32x32x16_bf16 v[82:97], v[240:243], v[178:181], v[82:97]
	s_waitcnt lgkmcnt(2)
	v_mfma_f32_32x32x16_bf16 v[66:81], v[244:247], v[178:181], v[66:81]
	s_waitcnt lgkmcnt(1)
	v_mfma_f32_32x32x16_bf16 v[82:97], v[248:251], v[182:185], v[82:97]
	s_waitcnt lgkmcnt(0)
	s_barrier
	v_mfma_f32_32x32x16_bf16 v[66:81], v[210:213], v[182:185], v[66:81]
	s_add_i32 s13, s11, -2
	s_cmp_ge_u32 s13, s5
	s_cbranch_scc1 .Latt2_ws_4
	s_waitcnt vmcnt(9)
	ds_write_b128 v219, v[118:121]
	s_waitcnt vmcnt(8)
	ds_write_b128 v220, v[122:125]
	s_waitcnt vmcnt(7)
	ds_write_b128 v221, v[130:133]
	s_waitcnt vmcnt(6)
	ds_write_b128 v222, v[134:137] offset:25600
	s_waitcnt vmcnt(5)
	ds_write_b128 v222, v[138:141] offset:34816
.Latt2_ws_4:
	s_cmp_ge_u32 s11, s5
	s_cbranch_scc1 .Latt2_wl_5
	v_add_co_u32_e32 v186, vcc, 0xffffc000, v206
	s_nop 1
	v_addc_co_u32_e32 v187, vcc, -1, v207, vcc
	global_load_dwordx4 v[118:121], v[186:187], off
	v_add_co_u32_e32 v186, vcc, 0xffffe000, v206
	s_nop 1
	v_addc_co_u32_e32 v187, vcc, -1, v207, vcc
	global_load_dwordx4 v[122:125], v[186:187], off
	global_load_dwordx4 v[130:133], v[206:207], off
	global_load_dwordx4 v[134:137], v[204:205], off offset:512
	global_load_dwordx4 v[138:141], v[208:209], off offset:512
.Latt2_wl_5:
	s_mov_b64 s[14:15], 0xc000
	v_lshl_add_u64 v[206:207], v[206:207], 0, s[14:15]
	s_mov_b64 s[14:15], 0x100
	s_add_i32 s11, s11, 2
	v_lshl_add_u64 v[204:205], v[204:205], 0, s[14:15]
	v_lshl_add_u64 v[208:209], v[208:209], 0, s[14:15]
	ds_read_b128 v[236:239], v217
	ds_read_b128 v[240:243], v217 offset:4608
	ds_read_b128 v[244:247], v217 offset:9216
	ds_read_b128 v[248:251], v217 offset:13824
	ds_read_b128 v[210:213], v217 offset:32
	s_nop 4
	v_max_f32_e32 v186, v83, v83
	v_max_f32_e32 v187, v82, v82
	v_max_f32_e32 v186, v187, v186
	v_max3_f32 v186, v186, v84, v85
	v_max3_f32 v186, v186, v86, v87
	v_max3_f32 v186, v186, v88, v89
	v_max3_f32 v186, v186, v90, v91
	v_max3_f32 v186, v186, v92, v93
	v_max3_f32 v186, v186, v94, v95
	v_max3_f32 v186, v186, v96, v97
	v_max3_f32 v186, v186, v66, v67
	v_max3_f32 v186, v186, v68, v69
	v_max3_f32 v186, v186, v70, v71
	v_max3_f32 v186, v186, v72, v73
	v_max3_f32 v186, v186, v74, v75
	v_max3_f32 v186, v186, v76, v77
	v_max3_f32 v186, v186, v78, v79
	v_max3_f32 v186, v186, v80, v81
	ds_bpermute_b32 v187, v214, v186
	s_waitcnt lgkmcnt(0)
	v_max_f32_e32 v187, v187, v187
	v_max_f32_e32 v187, v186, v187
	v_add_f32_e32 v186, 0x41380000, v223
	v_cmp_gt_f32_e32 vcc, v187, v186
	s_cbranch_vccz .Latt2_nr_6
	v_max_f32_e32 v186, v187, v187
	v_max_f32_e32 v187, v223, v223
	v_max_f32_e32 v187, v187, v186
	v_sub_f32_e32 v186, v223, v187
	v_exp_f32_e32 v186, v186
	v_mov_b32_e32 v223, v187
	v_pk_mul_f32 v[64:65], v[64:65], v[186:187] op_sel_hi:[1,0]
	v_pk_mul_f32 v[62:63], v[62:63], v[186:187] op_sel_hi:[1,0]
	v_pk_mul_f32 v[60:61], v[60:61], v[186:187] op_sel_hi:[1,0]
	v_pk_mul_f32 v[58:59], v[58:59], v[186:187] op_sel_hi:[1,0]
	v_pk_mul_f32 v[56:57], v[56:57], v[186:187] op_sel_hi:[1,0]
	v_pk_mul_f32 v[54:55], v[54:55], v[186:187] op_sel_hi:[1,0]
	v_pk_mul_f32 v[52:53], v[52:53], v[186:187] op_sel_hi:[1,0]
	v_pk_mul_f32 v[50:51], v[50:51], v[186:187] op_sel_hi:[1,0]
	v_pk_mul_f32 v[48:49], v[48:49], v[186:187] op_sel_hi:[1,0]
	v_pk_mul_f32 v[46:47], v[46:47], v[186:187] op_sel_hi:[1,0]
	v_pk_mul_f32 v[44:45], v[44:45], v[186:187] op_sel_hi:[1,0]
	v_pk_mul_f32 v[42:43], v[42:43], v[186:187] op_sel_hi:[1,0]
	v_pk_mul_f32 v[40:41], v[40:41], v[186:187] op_sel_hi:[1,0]
	v_pk_mul_f32 v[38:39], v[38:39], v[186:187] op_sel_hi:[1,0]
	v_pk_mul_f32 v[36:37], v[36:37], v[186:187] op_sel_hi:[1,0]
	v_pk_mul_f32 v[34:35], v[34:35], v[186:187] op_sel_hi:[1,0]
	v_pk_mul_f32 v[32:33], v[32:33], v[186:187] op_sel_hi:[1,0]
	v_pk_mul_f32 v[30:31], v[30:31], v[186:187] op_sel_hi:[1,0]
	v_pk_mul_f32 v[28:29], v[28:29], v[186:187] op_sel_hi:[1,0]
	v_pk_mul_f32 v[26:27], v[26:27], v[186:187] op_sel_hi:[1,0]
	v_pk_mul_f32 v[24:25], v[24:25], v[186:187] op_sel_hi:[1,0]
	v_pk_mul_f32 v[22:23], v[22:23], v[186:187] op_sel_hi:[1,0]
	v_pk_mul_f32 v[20:21], v[20:21], v[186:187] op_sel_hi:[1,0]
	v_pk_mul_f32 v[18:19], v[18:19], v[186:187] op_sel_hi:[1,0]
	v_pk_mul_f32 v[16:17], v[16:17], v[186:187] op_sel_hi:[1,0]
	v_pk_mul_f32 v[14:15], v[14:15], v[186:187] op_sel_hi:[1,0]
	v_pk_mul_f32 v[12:13], v[12:13], v[186:187] op_sel_hi:[1,0]
	v_pk_mul_f32 v[10:11], v[10:11], v[186:187] op_sel_hi:[1,0]
	v_pk_mul_f32 v[8:9], v[8:9], v[186:187] op_sel_hi:[1,0]
	v_pk_mul_f32 v[6:7], v[6:7], v[186:187] op_sel_hi:[1,0]
	v_pk_mul_f32 v[4:5], v[4:5], v[186:187] op_sel_hi:[1,0]
	v_pk_mul_f32 v[2:3], v[2:3], v[186:187] op_sel_hi:[1,0]
	v_mul_f32_e32 v225, v225, v186
.Latt2_nr_6:
	v_sub_f32_e32 v82, v82, v223
	v_sub_f32_e32 v83, v83, v223
	v_sub_f32_e32 v84, v84, v223
	v_sub_f32_e32 v85, v85, v223
	v_exp_f32_e32 v82, v82
	v_exp_f32_e32 v83, v83
	v_exp_f32_e32 v84, v84
	v_exp_f32_e32 v85, v85
	v_sub_f32_e32 v86, v86, v223
	v_sub_f32_e32 v87, v87, v223
	v_sub_f32_e32 v88, v88, v223
	v_sub_f32_e32 v89, v89, v223
	v_exp_f32_e32 v86, v86
	v_exp_f32_e32 v87, v87
	v_exp_f32_e32 v88, v88
	v_exp_f32_e32 v89, v89
	v_cvt_pk_bf16_f32 v226, v82, v83
	v_cvt_pk_bf16_f32 v227, v84, v85
	v_cvt_pk_bf16_f32 v228, v86, v87
	v_cvt_pk_bf16_f32 v229, v88, v89
	s_nop 1
	v_mfma_f32_32x32x16_bf16 v[50:65], v[236:239], v[226:229], v[50:65]
	ds_read_b128 v[236:239], v217 offset:4640
	v_sub_f32_e32 v90, v90, v223
	v_sub_f32_e32 v91, v91, v223
	v_sub_f32_e32 v92, v92, v223
	v_sub_f32_e32 v93, v93, v223
	v_exp_f32_e32 v90, v90
	v_exp_f32_e32 v91, v91
	v_mfma_f32_32x32x16_bf16 v[34:49], v[240:243], v[226:229], v[34:49]
	ds_read_b128 v[240:243], v217 offset:9248
	v_exp_f32_e32 v92, v92
	v_exp_f32_e32 v93, v93
	v_sub_f32_e32 v94, v94, v223
	v_sub_f32_e32 v95, v95, v223
	v_sub_f32_e32 v96, v96, v223
	v_sub_f32_e32 v97, v97, v223
	v_mfma_f32_32x32x16_bf16 v[18:33], v[244:247], v[226:229], v[18:33]
	ds_read_b128 v[244:247], v217 offset:13856
	v_exp_f32_e32 v94, v94
	v_exp_f32_e32 v95, v95
	v_exp_f32_e32 v96, v96
	v_exp_f32_e32 v97, v97
	v_add_f32_e32 v186, 0, v82
	v_add_f32_e32 v186, v83, v186
	v_mfma_f32_32x32x16_bf16 v[2:17], v[248:251], v[226:229], v[2:17]
	ds_read_b128 v[248:251], v217 offset:64
	v_add_f32_e32 v186, v84, v186
	v_add_f32_e32 v186, v85, v186
	v_add_f32_e32 v186, v86, v186
	v_add_f32_e32 v186, v87, v186
	v_add_f32_e32 v186, v88, v186
	v_add_f32_e32 v186, v89, v186
	v_cvt_pk_bf16_f32 v226, v90, v91
	v_cvt_pk_bf16_f32 v227, v92, v93
	v_cvt_pk_bf16_f32 v228, v94, v95
	v_cvt_pk_bf16_f32 v229, v96, v97
	s_nop 1
	v_mfma_f32_32x32x16_bf16 v[50:65], v[210:213], v[226:229], v[50:65]
	ds_read_b128 v[210:213], v217 offset:4672
	v_sub_f32_e32 v66, v66, v223
	v_sub_f32_e32 v67, v67, v223
	v_sub_f32_e32 v68, v68, v223
	v_sub_f32_e32 v69, v69, v223
	v_exp_f32_e32 v66, v66
	v_exp_f32_e32 v67, v67
	s_waitcnt lgkmcnt(4)
	v_mfma_f32_32x32x16_bf16 v[34:49], v[236:239], v[226:229], v[34:49]
	ds_read_b128 v[236:239], v217 offset:9280
	v_exp_f32_e32 v68, v68
	v_exp_f32_e32 v69, v69
	v_sub_f32_e32 v70, v70, v223
	v_sub_f32_e32 v71, v71, v223
	v_sub_f32_e32 v72, v72, v223
	v_sub_f32_e32 v73, v73, v223
	s_waitcnt lgkmcnt(4)
	v_mfma_f32_32x32x16_bf16 v[18:33], v[240:243], v[226:229], v[18:33]
	ds_read_b128 v[240:243], v217 offset:13888
	v_exp_f32_e32 v70, v70
	v_exp_f32_e32 v71, v71
	v_exp_f32_e32 v72, v72
	v_exp_f32_e32 v73, v73
	v_add_f32_e32 v186, v90, v186
	v_add_f32_e32 v186, v91, v186
	s_waitcnt lgkmcnt(4)
	v_mfma_f32_32x32x16_bf16 v[2:17], v[244:247], v[226:229], v[2:17]
	ds_read_b128 v[244:247], v217 offset:96
	v_add_f32_e32 v186, v92, v186
	v_add_f32_e32 v186, v93, v186
	v_add_f32_e32 v186, v94, v186
	v_add_f32_e32 v186, v95, v186
	v_add_f32_e32 v186, v96, v186
	v_add_f32_e32 v186, v97, v186
	v_cvt_pk_bf16_f32 v226, v66, v67
	v_cvt_pk_bf16_f32 v227, v68, v69
	v_cvt_pk_bf16_f32 v228, v70, v71
	v_cvt_pk_bf16_f32 v229, v72, v73
	s_nop 1
	s_waitcnt lgkmcnt(4)
	v_mfma_f32_32x32x16_bf16 v[50:65], v[248:251], v[226:229], v[50:65]
	ds_read_b128 v[248:251], v217 offset:4704
	v_sub_f32_e32 v74, v74, v223
	v_sub_f32_e32 v75, v75, v223
	v_sub_f32_e32 v76, v76, v223
	v_sub_f32_e32 v77, v77, v223
	v_exp_f32_e32 v74, v74
	v_exp_f32_e32 v75, v75
	s_waitcnt lgkmcnt(4)
	v_mfma_f32_32x32x16_bf16 v[34:49], v[210:213], v[226:229], v[34:49]
	ds_read_b128 v[210:213], v217 offset:9312
	v_exp_f32_e32 v76, v76
	v_exp_f32_e32 v77, v77
	v_sub_f32_e32 v78, v78, v223
	v_sub_f32_e32 v79, v79, v223
	v_sub_f32_e32 v80, v80, v223
	v_sub_f32_e32 v81, v81, v223
	s_waitcnt lgkmcnt(4)
	v_mfma_f32_32x32x16_bf16 v[18:33], v[236:239], v[226:229], v[18:33]
	ds_read_b128 v[236:239], v217 offset:13920
	v_exp_f32_e32 v78, v78
	v_exp_f32_e32 v79, v79
	v_exp_f32_e32 v80, v80
	v_exp_f32_e32 v81, v81
	v_add_f32_e32 v186, v66, v186
	v_add_f32_e32 v186, v67, v186
	s_waitcnt lgkmcnt(4)
	v_mfma_f32_32x32x16_bf16 v[2:17], v[240:243], v[226:229], v[2:17]
	v_add_f32_e32 v186, v68, v186
	v_add_f32_e32 v186, v69, v186
	v_add_f32_e32 v186, v70, v186
	v_add_f32_e32 v186, v71, v186
	v_add_f32_e32 v186, v72, v186
	v_add_f32_e32 v186, v73, v186
	v_cvt_pk_bf16_f32 v226, v74, v75
	v_cvt_pk_bf16_f32 v227, v76, v77
	v_cvt_pk_bf16_f32 v228, v78, v79
	v_cvt_pk_bf16_f32 v229, v80, v81
	s_nop 1
	s_waitcnt lgkmcnt(3)
	v_mfma_f32_32x32x16_bf16 v[50:65], v[244:247], v[226:229], v[50:65]
	v_add_f32_e32 v186, v74, v186
	v_add_f32_e32 v186, v75, v186
	s_waitcnt lgkmcnt(2)
	v_mfma_f32_32x32x16_bf16 v[34:49], v[248:251], v[226:229], v[34:49]
	v_add_f32_e32 v186, v76, v186
	v_add_f32_e32 v186, v77, v186
	s_waitcnt lgkmcnt(1)
	v_mfma_f32_32x32x16_bf16 v[18:33], v[210:213], v[226:229], v[18:33]
	v_add_f32_e32 v186, v78, v186
	v_add_f32_e32 v186, v79, v186
	s_waitcnt lgkmcnt(0)
	s_barrier
	v_mfma_f32_32x32x16_bf16 v[2:17], v[236:239], v[226:229], v[2:17]
	v_add_f32_e32 v186, v80, v186
	v_add_f32_e32 v186, v81, v186
	v_add_f32_e32 v224, v225, v186
	s_add_i32 s13, s11, -4
	s_cmp_ge_u32 s13, s5
	s_cbranch_scc0 .Latt2_A_loop
	s_branch .LBB0_40
.Latt2_B_pro:
	s_barrier
	s_add_i32 s13, s11, -1
	s_cmp_ge_u32 s13, s5
	s_cbranch_scc1 .Latt2_wt_7
	s_waitcnt vmcnt(9)
	ds_write_b128 v219, v[102:105] offset:44032
	s_waitcnt vmcnt(8)
	ds_write_b128 v220, v[106:109] offset:44032
	s_waitcnt vmcnt(7)
	ds_write_b128 v221, v[114:117] offset:44032
	s_waitcnt vmcnt(6)
	ds_write_b128 v201, v[98:101]
	s_waitcnt vmcnt(5)
	ds_write_b128 v201, v[110:113] offset:9216
	v_add_co_u32_e32 v186, vcc, 0xffff6000, v206
	s_nop 1
	v_addc_co_u32_e32 v187, vcc, -1, v207, vcc
	global_load_dwordx4 v[102:105], v[186:187], off
	v_add_co_u32_e32 v186, vcc, 0xffff8000, v206
	s_nop 1
	v_addc_co_u32_e32 v187, vcc, -1, v207, vcc
	global_load_dwordx4 v[106:109], v[186:187], off
	v_add_co_u32_e32 v186, vcc, 0xffffa000, v206
	s_nop 1
	v_addc_co_u32_e32 v187, vcc, -1, v207, vcc
	global_load_dwordx4 v[114:117], v[186:187], off
	global_load_dwordx4 v[98:101], v[204:205], off offset:384
	global_load_dwordx4 v[110:113], v[208:209], off offset:384
	s_branch .Latt2_wd_8

.Latt2_wd_8:
	ds_read_b128 v[226:229], v215
	ds_read_b128 v[236:239], v215 offset:12800
	ds_read_b128 v[240:243], v215 offset:32
	ds_read_b128 v[244:247], v215 offset:12832
	ds_read_b128 v[248:251], v215 offset:64
	ds_read_b128 v[210:213], v215 offset:12864
	s_waitcnt lgkmcnt(5)
	v_mfma_f32_32x32x16_bf16 v[82:97], v[226:229], v[126:129], 0
	ds_read_b128 v[226:229], v215 offset:96
	s_waitcnt lgkmcnt(5)
	v_mfma_f32_32x32x16_bf16 v[66:81], v[236:239], v[126:129], 0
	ds_read_b128 v[236:239], v215 offset:12896
	s_waitcnt lgkmcnt(5)
	v_mfma_f32_32x32x16_bf16 v[82:97], v[240:243], v[142:145], v[82:97]
	ds_read_b128 v[240:243], v215 offset:128
	s_waitcnt lgkmcnt(5)
	v_mfma_f32_32x32x16_bf16 v[66:81], v[244:247], v[142:145], v[66:81]
	ds_read_b128 v[244:247], v215 offset:12928
	s_waitcnt lgkmcnt(5)
	v_mfma_f32_32x32x16_bf16 v[82:97], v[248:251], v[146:149], v[82:97]
	ds_read_b128 v[248:251], v215 offset:160
	s_waitcnt lgkmcnt(5)
	v_mfma_f32_32x32x16_bf16 v[66:81], v[210:213], v[146:149], v[66:81]
	ds_read_b128 v[210:213], v215 offset:12960
	s_waitcnt lgkmcnt(5)
	v_mfma_f32_32x32x16_bf16 v[82:97], v[226:229], v[150:153], v[82:97]
	ds_read_b128 v[226:229], v215 offset:192
	s_waitcnt lgkmcnt(5)
	v_mfma_f32_32x32x16_bf16 v[66:81], v[236:239], v[150:153], v[66:81]
	ds_read_b128 v[236:239], v215 offset:12992
	s_waitcnt lgkmcnt(5)
	v_mfma_f32_32x32x16_bf16 v[82:97], v[240:243], v[154:157], v[82:97]
	ds_read_b128 v[240:243], v215 offset:224
	s_waitcnt lgkmcnt(5)
	v_mfma_f32_32x32x16_bf16 v[66:81], v[244:247], v[154:157], v[66:81]
	ds_read_b128 v[244:247], v215 offset:13024
	s_waitcnt lgkmcnt(5)
	v_mfma_f32_32x32x16_bf16 v[82:97], v[248:251], v[158:161], v[82:97]
	ds_read_b128 v[248:251], v215 offset:256
	s_waitcnt lgkmcnt(5)
	v_mfma_f32_32x32x16_bf16 v[66:81], v[210:213], v[158:161], v[66:81]
	ds_read_b128 v[210:213], v215 offset:13056
	s_waitcnt lgkmcnt(5)
	v_mfma_f32_32x32x16_bf16 v[82:97], v[226:229], v[162:165], v[82:97]
	ds_read_b128 v[226:229], v215 offset:288
	s_waitcnt lgkmcnt(5)
	v_mfma_f32_32x32x16_bf16 v[66:81], v[236:239], v[162:165], v[66:81]
	ds_read_b128 v[236:239], v215 offset:13088
	s_waitcnt lgkmcnt(5)
	v_mfma_f32_32x32x16_bf16 v[82:97], v[240:243], v[166:169], v[82:97]
	ds_read_b128 v[240:243], v215 offset:320
	s_waitcnt lgkmcnt(5)
	v_mfma_f32_32x32x16_bf16 v[66:81], v[244:247], v[166:169], v[66:81]
	ds_read_b128 v[244:247], v215 offset:13120
	s_waitcnt lgkmcnt(5)
	v_mfma_f32_32x32x16_bf16 v[82:97], v[248:251], v[170:173], v[82:97]
	ds_read_b128 v[248:251], v215 offset:352
	s_waitcnt lgkmcnt(5)
	v_mfma_f32_32x32x16_bf16 v[66:81], v[210:213], v[170:173], v[66:81]
	ds_read_b128 v[210:213], v215 offset:13152
	s_waitcnt lgkmcnt(5)
	v_mfma_f32_32x32x16_bf16 v[82:97], v[226:229], v[174:177], v[82:97]
	s_waitcnt lgkmcnt(4)
	v_mfma_f32_32x32x16_bf16 v[66:81], v[236:239], v[174:177], v[66:81]
	s_waitcnt lgkmcnt(3)
	v_mfma_f32_32x32x16_bf16 v[82:97], v[240:243], v[178:181], v[82:97]
	s_waitcnt lgkmcnt(2)
	v_mfma_f32_32x32x16_bf16 v[66:81], v[244:247], v[178:181], v[66:81]
	s_waitcnt lgkmcnt(1)
	v_mfma_f32_32x32x16_bf16 v[82:97], v[248:251], v[182:185], v[82:97]
	s_waitcnt lgkmcnt(0)
	s_barrier
	v_mfma_f32_32x32x16_bf16 v[66:81], v[210:213], v[182:185], v[66:81]

.Latt2_nr_9:
	v_sub_f32_e32 v82, v82, v223
	v_sub_f32_e32 v83, v83, v223
	v_sub_f32_e32 v84, v84, v223
	v_sub_f32_e32 v85, v85, v223
	v_exp_f32_e32 v82, v82
	v_exp_f32_e32 v83, v83
	v_exp_f32_e32 v84, v84
	v_exp_f32_e32 v85, v85
	v_sub_f32_e32 v86, v86, v223
	v_sub_f32_e32 v87, v87, v223
	v_sub_f32_e32 v88, v88, v223
	v_sub_f32_e32 v89, v89, v223
	v_exp_f32_e32 v86, v86
	v_exp_f32_e32 v87, v87
	v_exp_f32_e32 v88, v88
	v_exp_f32_e32 v89, v89
	v_cvt_pk_bf16_f32 v226, v82, v83
	v_cvt_pk_bf16_f32 v227, v84, v85
	v_cvt_pk_bf16_f32 v228, v86, v87
	v_cvt_pk_bf16_f32 v229, v88, v89
	s_nop 1
	v_mfma_f32_32x32x16_bf16 v[50:65], v[236:239], v[226:229], v[50:65]
	ds_read_b128 v[236:239], v216 offset:30240
	v_sub_f32_e32 v90, v90, v223
	v_sub_f32_e32 v91, v91, v223
	v_sub_f32_e32 v92, v92, v223
	v_sub_f32_e32 v93, v93, v223
	v_exp_f32_e32 v90, v90
	v_exp_f32_e32 v91, v91
	v_mfma_f32_32x32x16_bf16 v[34:49], v[240:243], v[226:229], v[34:49]
	ds_read_b128 v[240:243], v216 offset:34848
	v_exp_f32_e32 v92, v92
	v_exp_f32_e32 v93, v93
	v_sub_f32_e32 v94, v94, v223
	v_sub_f32_e32 v95, v95, v223
	v_sub_f32_e32 v96, v96, v223
	v_sub_f32_e32 v97, v97, v223
	v_mfma_f32_32x32x16_bf16 v[18:33], v[244:247], v[226:229], v[18:33]
	ds_read_b128 v[244:247], v216 offset:39456
	v_exp_f32_e32 v94, v94
	v_exp_f32_e32 v95, v95
	v_exp_f32_e32 v96, v96
	v_exp_f32_e32 v97, v97
	v_add_f32_e32 v186, 0, v82
	v_add_f32_e32 v186, v83, v186
	v_mfma_f32_32x32x16_bf16 v[2:17], v[248:251], v[226:229], v[2:17]
	ds_read_b128 v[248:251], v216 offset:25664
	v_add_f32_e32 v186, v84, v186
	v_add_f32_e32 v186, v85, v186
	v_add_f32_e32 v186, v86, v186
	v_add_f32_e32 v186, v87, v186
	v_add_f32_e32 v186, v88, v186
	v_add_f32_e32 v186, v89, v186
	v_cvt_pk_bf16_f32 v226, v90, v91
	v_cvt_pk_bf16_f32 v227, v92, v93
	v_cvt_pk_bf16_f32 v228, v94, v95
	v_cvt_pk_bf16_f32 v229, v96, v97
	s_nop 1
	v_mfma_f32_32x32x16_bf16 v[50:65], v[210:213], v[226:229], v[50:65]
	ds_read_b128 v[210:213], v216 offset:30272
	v_sub_f32_e32 v66, v66, v223
	v_sub_f32_e32 v67, v67, v223
	v_sub_f32_e32 v68, v68, v223
	v_sub_f32_e32 v69, v69, v223
	v_exp_f32_e32 v66, v66
	v_exp_f32_e32 v67, v67
	s_waitcnt lgkmcnt(4)
	v_mfma_f32_32x32x16_bf16 v[34:49], v[236:239], v[226:229], v[34:49]
	ds_read_b128 v[236:239], v216 offset:34880
	v_exp_f32_e32 v68, v68
	v_exp_f32_e32 v69, v69
	v_sub_f32_e32 v70, v70, v223
	v_sub_f32_e32 v71, v71, v223
	v_sub_f32_e32 v72, v72, v223
	v_sub_f32_e32 v73, v73, v223
	s_waitcnt lgkmcnt(4)
	v_mfma_f32_32x32x16_bf16 v[18:33], v[240:243], v[226:229], v[18:33]
	ds_read_b128 v[240:243], v216 offset:39488
	v_exp_f32_e32 v70, v70
	v_exp_f32_e32 v71, v71
	v_exp_f32_e32 v72, v72
	v_exp_f32_e32 v73, v73
	v_add_f32_e32 v186, v90, v186
	v_add_f32_e32 v186, v91, v186
	s_waitcnt lgkmcnt(4)
	v_mfma_f32_32x32x16_bf16 v[2:17], v[244:247], v[226:229], v[2:17]
	ds_read_b128 v[244:247], v216 offset:25696
	v_add_f32_e32 v186, v92, v186
	v_add_f32_e32 v186, v93, v186
	v_add_f32_e32 v186, v94, v186
	v_add_f32_e32 v186, v95, v186
	v_add_f32_e32 v186, v96, v186
	v_add_f32_e32 v186, v97, v186
	v_cvt_pk_bf16_f32 v226, v66, v67
	v_cvt_pk_bf16_f32 v227, v68, v69
	v_cvt_pk_bf16_f32 v228, v70, v71
	v_cvt_pk_bf16_f32 v229, v72, v73
	s_nop 1
	s_waitcnt lgkmcnt(4)
	v_mfma_f32_32x32x16_bf16 v[50:65], v[248:251], v[226:229], v[50:65]
	ds_read_b128 v[248:251], v216 offset:30304
	v_sub_f32_e32 v74, v74, v223
	v_sub_f32_e32 v75, v75, v223
	v_sub_f32_e32 v76, v76, v223
	v_sub_f32_e32 v77, v77, v223
	v_exp_f32_e32 v74, v74
	v_exp_f32_e32 v75, v75
	s_waitcnt lgkmcnt(4)
	v_mfma_f32_32x32x16_bf16 v[34:49], v[210:213], v[226:229], v[34:49]
	ds_read_b128 v[210:213], v216 offset:34912
	v_exp_f32_e32 v76, v76
	v_exp_f32_e32 v77, v77
	v_sub_f32_e32 v78, v78, v223
	v_sub_f32_e32 v79, v79, v223
	v_sub_f32_e32 v80, v80, v223
	v_sub_f32_e32 v81, v81, v223
	s_waitcnt lgkmcnt(4)
	v_mfma_f32_32x32x16_bf16 v[18:33], v[236:239], v[226:229], v[18:33]
	ds_read_b128 v[236:239], v216 offset:39520
	v_exp_f32_e32 v78, v78
	v_exp_f32_e32 v79, v79
	v_exp_f32_e32 v80, v80
	v_exp_f32_e32 v81, v81
	v_add_f32_e32 v186, v66, v186
	v_add_f32_e32 v186, v67, v186
	s_waitcnt lgkmcnt(4)
	v_mfma_f32_32x32x16_bf16 v[2:17], v[240:243], v[226:229], v[2:17]
	v_add_f32_e32 v186, v68, v186
	v_add_f32_e32 v186, v69, v186
	v_add_f32_e32 v186, v70, v186
	v_add_f32_e32 v186, v71, v186
	v_add_f32_e32 v186, v72, v186
	v_add_f32_e32 v186, v73, v186
	v_cvt_pk_bf16_f32 v226, v74, v75
	v_cvt_pk_bf16_f32 v227, v76, v77
	v_cvt_pk_bf16_f32 v228, v78, v79
	v_cvt_pk_bf16_f32 v229, v80, v81
	s_nop 1
	s_waitcnt lgkmcnt(3)
	v_mfma_f32_32x32x16_bf16 v[50:65], v[244:247], v[226:229], v[50:65]
	v_add_f32_e32 v186, v74, v186
	v_add_f32_e32 v186, v75, v186
	s_waitcnt lgkmcnt(2)
	v_mfma_f32_32x32x16_bf16 v[34:49], v[248:251], v[226:229], v[34:49]
	v_add_f32_e32 v186, v76, v186
	v_add_f32_e32 v186, v77, v186
	s_waitcnt lgkmcnt(1)
	v_mfma_f32_32x32x16_bf16 v[18:33], v[210:213], v[226:229], v[18:33]
	v_add_f32_e32 v186, v78, v186
	v_add_f32_e32 v186, v79, v186
	s_waitcnt lgkmcnt(0)
	s_barrier
	v_mfma_f32_32x32x16_bf16 v[2:17], v[236:239], v[226:229], v[2:17]
	v_add_f32_e32 v186, v80, v186
	v_add_f32_e32 v186, v81, v186
	v_add_f32_e32 v225, v224, v186
	s_add_i32 s13, s11, -2
	s_cmp_ge_u32 s13, s5
	s_cbranch_scc1 .Latt2_ws_10
	s_waitcnt vmcnt(9)
	ds_write_b128 v219, v[118:121]
	s_waitcnt vmcnt(8)
	ds_write_b128 v220, v[122:125]
	s_waitcnt vmcnt(7)
	ds_write_b128 v221, v[130:133]
	s_waitcnt vmcnt(6)
	ds_write_b128 v222, v[134:137] offset:25600
	s_waitcnt vmcnt(5)
	ds_write_b128 v222, v[138:141] offset:34816

.Latt2_wl_11:
	s_mov_b64 s[14:15], 0xc000
	v_lshl_add_u64 v[206:207], v[206:207], 0, s[14:15]
	s_mov_b64 s[14:15], 0x100
	s_add_i32 s11, s11, 2
	v_lshl_add_u64 v[204:205], v[204:205], 0, s[14:15]
	v_lshl_add_u64 v[208:209], v[208:209], 0, s[14:15]
	ds_read_b128 v[226:229], v215 offset:44032
	ds_read_b128 v[236:239], v215 offset:56832
	ds_read_b128 v[240:243], v215 offset:44064
	ds_read_b128 v[244:247], v215 offset:56864
	ds_read_b128 v[248:251], v215 offset:44096
	ds_read_b128 v[210:213], v215 offset:56896
	s_waitcnt lgkmcnt(5)
	v_mfma_f32_32x32x16_bf16 v[82:97], v[226:229], v[126:129], 0
	ds_read_b128 v[226:229], v215 offset:44128
	s_waitcnt lgkmcnt(5)
	v_mfma_f32_32x32x16_bf16 v[66:81], v[236:239], v[126:129], 0
	ds_read_b128 v[236:239], v215 offset:56928
	s_waitcnt lgkmcnt(5)
	v_mfma_f32_32x32x16_bf16 v[82:97], v[240:243], v[142:145], v[82:97]
	ds_read_b128 v[240:243], v215 offset:44160
	s_waitcnt lgkmcnt(5)
	v_mfma_f32_32x32x16_bf16 v[66:81], v[244:247], v[142:145], v[66:81]
	ds_read_b128 v[244:247], v215 offset:56960
	s_waitcnt lgkmcnt(5)
	v_mfma_f32_32x32x16_bf16 v[82:97], v[248:251], v[146:149], v[82:97]
	ds_read_b128 v[248:251], v215 offset:44192
	s_waitcnt lgkmcnt(5)
	v_mfma_f32_32x32x16_bf16 v[66:81], v[210:213], v[146:149], v[66:81]
	ds_read_b128 v[210:213], v215 offset:56992
	s_waitcnt lgkmcnt(5)
	v_mfma_f32_32x32x16_bf16 v[82:97], v[226:229], v[150:153], v[82:97]
	ds_read_b128 v[226:229], v215 offset:44224
	s_waitcnt lgkmcnt(5)
	v_mfma_f32_32x32x16_bf16 v[66:81], v[236:239], v[150:153], v[66:81]
	ds_read_b128 v[236:239], v215 offset:57024
	s_waitcnt lgkmcnt(5)
	v_mfma_f32_32x32x16_bf16 v[82:97], v[240:243], v[154:157], v[82:97]
	ds_read_b128 v[240:243], v215 offset:44256
	s_waitcnt lgkmcnt(5)
	v_mfma_f32_32x32x16_bf16 v[66:81], v[244:247], v[154:157], v[66:81]
	ds_read_b128 v[244:247], v215 offset:57056
	s_waitcnt lgkmcnt(5)
	v_mfma_f32_32x32x16_bf16 v[82:97], v[248:251], v[158:161], v[82:97]
	ds_read_b128 v[248:251], v215 offset:44288
	s_waitcnt lgkmcnt(5)
	v_mfma_f32_32x32x16_bf16 v[66:81], v[210:213], v[158:161], v[66:81]
	ds_read_b128 v[210:213], v215 offset:57088
	s_waitcnt lgkmcnt(5)
	v_mfma_f32_32x32x16_bf16 v[82:97], v[226:229], v[162:165], v[82:97]
	ds_read_b128 v[226:229], v215 offset:44320
	s_waitcnt lgkmcnt(5)
	v_mfma_f32_32x32x16_bf16 v[66:81], v[236:239], v[162:165], v[66:81]
	ds_read_b128 v[236:239], v215 offset:57120
	s_waitcnt lgkmcnt(5)
	v_mfma_f32_32x32x16_bf16 v[82:97], v[240:243], v[166:169], v[82:97]
	ds_read_b128 v[240:243], v215 offset:44352
	s_waitcnt lgkmcnt(5)
	v_mfma_f32_32x32x16_bf16 v[66:81], v[244:247], v[166:169], v[66:81]
	ds_read_b128 v[244:247], v215 offset:57152
	s_waitcnt lgkmcnt(5)
	v_mfma_f32_32x32x16_bf16 v[82:97], v[248:251], v[170:173], v[82:97]
	ds_read_b128 v[248:251], v215 offset:44384
	s_waitcnt lgkmcnt(5)
	v_mfma_f32_32x32x16_bf16 v[66:81], v[210:213], v[170:173], v[66:81]
	ds_read_b128 v[210:213], v215 offset:57184
	s_waitcnt lgkmcnt(5)
	v_mfma_f32_32x32x16_bf16 v[82:97], v[226:229], v[174:177], v[82:97]
	s_waitcnt lgkmcnt(4)
	v_mfma_f32_32x32x16_bf16 v[66:81], v[236:239], v[174:177], v[66:81]
	s_waitcnt lgkmcnt(3)
	v_mfma_f32_32x32x16_bf16 v[82:97], v[240:243], v[178:181], v[82:97]
	s_waitcnt lgkmcnt(2)
	v_mfma_f32_32x32x16_bf16 v[66:81], v[244:247], v[178:181], v[66:81]
	s_waitcnt lgkmcnt(1)
	v_mfma_f32_32x32x16_bf16 v[82:97], v[248:251], v[182:185], v[82:97]
	s_waitcnt lgkmcnt(0)
	s_barrier
	v_mfma_f32_32x32x16_bf16 v[66:81], v[210:213], v[182:185], v[66:81]
	ds_read_b128 v[236:239], v217
	ds_read_b128 v[240:243], v217 offset:4608
	ds_read_b128 v[244:247], v217 offset:9216
	ds_read_b128 v[248:251], v217 offset:13824
	ds_read_b128 v[210:213], v217 offset:32
	s_nop 4
	v_max_f32_e32 v186, v83, v83
	v_max_f32_e32 v187, v82, v82
	v_max_f32_e32 v186, v187, v186
	v_max3_f32 v186, v186, v84, v85
	v_max3_f32 v186, v186, v86, v87
	v_max3_f32 v186, v186, v88, v89
	v_max3_f32 v186, v186, v90, v91
	v_max3_f32 v186, v186, v92, v93
	v_max3_f32 v186, v186, v94, v95
	v_max3_f32 v186, v186, v96, v97
	v_max3_f32 v186, v186, v66, v67
	v_max3_f32 v186, v186, v68, v69
	v_max3_f32 v186, v186, v70, v71
	v_max3_f32 v186, v186, v72, v73
	v_max3_f32 v186, v186, v74, v75
	v_max3_f32 v186, v186, v76, v77
	v_max3_f32 v186, v186, v78, v79
	v_max3_f32 v186, v186, v80, v81
	ds_bpermute_b32 v187, v214, v186
	s_waitcnt lgkmcnt(0)
	v_max_f32_e32 v187, v187, v187
	v_max_f32_e32 v187, v186, v187
	v_add_f32_e32 v186, 0x41380000, v223
	v_cmp_gt_f32_e32 vcc, v187, v186
	s_cbranch_vccz .Latt2_nr_12
	v_max_f32_e32 v186, v187, v187
	v_max_f32_e32 v187, v223, v223
	v_max_f32_e32 v187, v187, v186
	v_sub_f32_e32 v186, v223, v187
	v_exp_f32_e32 v186, v186
	v_mov_b32_e32 v223, v187
	v_pk_mul_f32 v[64:65], v[64:65], v[186:187] op_sel_hi:[1,0]
	v_pk_mul_f32 v[62:63], v[62:63], v[186:187] op_sel_hi:[1,0]
	v_pk_mul_f32 v[60:61], v[60:61], v[186:187] op_sel_hi:[1,0]
	v_pk_mul_f32 v[58:59], v[58:59], v[186:187] op_sel_hi:[1,0]
	v_pk_mul_f32 v[56:57], v[56:57], v[186:187] op_sel_hi:[1,0]
	v_pk_mul_f32 v[54:55], v[54:55], v[186:187] op_sel_hi:[1,0]
	v_pk_mul_f32 v[52:53], v[52:53], v[186:187] op_sel_hi:[1,0]
	v_pk_mul_f32 v[50:51], v[50:51], v[186:187] op_sel_hi:[1,0]
	v_pk_mul_f32 v[48:49], v[48:49], v[186:187] op_sel_hi:[1,0]
	v_pk_mul_f32 v[46:47], v[46:47], v[186:187] op_sel_hi:[1,0]
	v_pk_mul_f32 v[44:45], v[44:45], v[186:187] op_sel_hi:[1,0]
	v_pk_mul_f32 v[42:43], v[42:43], v[186:187] op_sel_hi:[1,0]
	v_pk_mul_f32 v[40:41], v[40:41], v[186:187] op_sel_hi:[1,0]
	v_pk_mul_f32 v[38:39], v[38:39], v[186:187] op_sel_hi:[1,0]
	v_pk_mul_f32 v[36:37], v[36:37], v[186:187] op_sel_hi:[1,0]
	v_pk_mul_f32 v[34:35], v[34:35], v[186:187] op_sel_hi:[1,0]
	v_pk_mul_f32 v[32:33], v[32:33], v[186:187] op_sel_hi:[1,0]
	v_pk_mul_f32 v[30:31], v[30:31], v[186:187] op_sel_hi:[1,0]
	v_pk_mul_f32 v[28:29], v[28:29], v[186:187] op_sel_hi:[1,0]
	v_pk_mul_f32 v[26:27], v[26:27], v[186:187] op_sel_hi:[1,0]
	v_pk_mul_f32 v[24:25], v[24:25], v[186:187] op_sel_hi:[1,0]
	v_pk_mul_f32 v[22:23], v[22:23], v[186:187] op_sel_hi:[1,0]
	v_pk_mul_f32 v[20:21], v[20:21], v[186:187] op_sel_hi:[1,0]
	v_pk_mul_f32 v[18:19], v[18:19], v[186:187] op_sel_hi:[1,0]
	v_pk_mul_f32 v[16:17], v[16:17], v[186:187] op_sel_hi:[1,0]
	v_pk_mul_f32 v[14:15], v[14:15], v[186:187] op_sel_hi:[1,0]
	v_pk_mul_f32 v[12:13], v[12:13], v[186:187] op_sel_hi:[1,0]
	v_pk_mul_f32 v[10:11], v[10:11], v[186:187] op_sel_hi:[1,0]
	v_pk_mul_f32 v[8:9], v[8:9], v[186:187] op_sel_hi:[1,0]
	v_pk_mul_f32 v[6:7], v[6:7], v[186:187] op_sel_hi:[1,0]
	v_pk_mul_f32 v[4:5], v[4:5], v[186:187] op_sel_hi:[1,0]
	v_pk_mul_f32 v[2:3], v[2:3], v[186:187] op_sel_hi:[1,0]
	v_mul_f32_e32 v225, v225, v186
.Latt2_nr_12:
	v_sub_f32_e32 v82, v82, v223
	v_sub_f32_e32 v83, v83, v223
	v_sub_f32_e32 v84, v84, v223
	v_sub_f32_e32 v85, v85, v223
	v_exp_f32_e32 v82, v82
	v_exp_f32_e32 v83, v83
	v_exp_f32_e32 v84, v84
	v_exp_f32_e32 v85, v85
	v_sub_f32_e32 v86, v86, v223
	v_sub_f32_e32 v87, v87, v223
	v_sub_f32_e32 v88, v88, v223
	v_sub_f32_e32 v89, v89, v223
	v_exp_f32_e32 v86, v86
	v_exp_f32_e32 v87, v87
	v_exp_f32_e32 v88, v88
	v_exp_f32_e32 v89, v89
	v_cvt_pk_bf16_f32 v226, v82, v83
	v_cvt_pk_bf16_f32 v227, v84, v85
	v_cvt_pk_bf16_f32 v228, v86, v87
	v_cvt_pk_bf16_f32 v229, v88, v89
	s_nop 1
	v_mfma_f32_32x32x16_bf16 v[50:65], v[236:239], v[226:229], v[50:65]
	ds_read_b128 v[236:239], v217 offset:4640
	v_sub_f32_e32 v90, v90, v223
	v_sub_f32_e32 v91, v91, v223
	v_sub_f32_e32 v92, v92, v223
	v_sub_f32_e32 v93, v93, v223
	v_exp_f32_e32 v90, v90
	v_exp_f32_e32 v91, v91
	v_mfma_f32_32x32x16_bf16 v[34:49], v[240:243], v[226:229], v[34:49]
	ds_read_b128 v[240:243], v217 offset:9248
	v_exp_f32_e32 v92, v92
	v_exp_f32_e32 v93, v93
	v_sub_f32_e32 v94, v94, v223
	v_sub_f32_e32 v95, v95, v223
	v_sub_f32_e32 v96, v96, v223
	v_sub_f32_e32 v97, v97, v223
	v_mfma_f32_32x32x16_bf16 v[18:33], v[244:247], v[226:229], v[18:33]
	ds_read_b128 v[244:247], v217 offset:13856
	v_exp_f32_e32 v94, v94
	v_exp_f32_e32 v95, v95
	v_exp_f32_e32 v96, v96
	v_exp_f32_e32 v97, v97
	v_add_f32_e32 v186, 0, v82
	v_add_f32_e32 v186, v83, v186
	v_mfma_f32_32x32x16_bf16 v[2:17], v[248:251], v[226:229], v[2:17]
	ds_read_b128 v[248:251], v217 offset:64
	v_add_f32_e32 v186, v84, v186
	v_add_f32_e32 v186, v85, v186
	v_add_f32_e32 v186, v86, v186
	v_add_f32_e32 v186, v87, v186
	v_add_f32_e32 v186, v88, v186
	v_add_f32_e32 v186, v89, v186
	v_cvt_pk_bf16_f32 v226, v90, v91
	v_cvt_pk_bf16_f32 v227, v92, v93
	v_cvt_pk_bf16_f32 v228, v94, v95
	v_cvt_pk_bf16_f32 v229, v96, v97
	s_nop 1
	v_mfma_f32_32x32x16_bf16 v[50:65], v[210:213], v[226:229], v[50:65]
	ds_read_b128 v[210:213], v217 offset:4672
	v_sub_f32_e32 v66, v66, v223
	v_sub_f32_e32 v67, v67, v223
	v_sub_f32_e32 v68, v68, v223
	v_sub_f32_e32 v69, v69, v223
	v_exp_f32_e32 v66, v66
	v_exp_f32_e32 v67, v67
	s_waitcnt lgkmcnt(4)
	v_mfma_f32_32x32x16_bf16 v[34:49], v[236:239], v[226:229], v[34:49]
	ds_read_b128 v[236:239], v217 offset:9280
	v_exp_f32_e32 v68, v68
	v_exp_f32_e32 v69, v69
	v_sub_f32_e32 v70, v70, v223
	v_sub_f32_e32 v71, v71, v223
	v_sub_f32_e32 v72, v72, v223
	v_sub_f32_e32 v73, v73, v223
	s_waitcnt lgkmcnt(4)
	v_mfma_f32_32x32x16_bf16 v[18:33], v[240:243], v[226:229], v[18:33]
	ds_read_b128 v[240:243], v217 offset:13888
	v_exp_f32_e32 v70, v70
	v_exp_f32_e32 v71, v71
	v_exp_f32_e32 v72, v72
	v_exp_f32_e32 v73, v73
	v_add_f32_e32 v186, v90, v186
	v_add_f32_e32 v186, v91, v186
	s_waitcnt lgkmcnt(4)
	v_mfma_f32_32x32x16_bf16 v[2:17], v[244:247], v[226:229], v[2:17]
	ds_read_b128 v[244:247], v217 offset:96
	v_add_f32_e32 v186, v92, v186
	v_add_f32_e32 v186, v93, v186
	v_add_f32_e32 v186, v94, v186
	v_add_f32_e32 v186, v95, v186
	v_add_f32_e32 v186, v96, v186
	v_add_f32_e32 v186, v97, v186
	v_cvt_pk_bf16_f32 v226, v66, v67
	v_cvt_pk_bf16_f32 v227, v68, v69
	v_cvt_pk_bf16_f32 v228, v70, v71
	v_cvt_pk_bf16_f32 v229, v72, v73
	s_nop 1
	s_waitcnt lgkmcnt(4)
	v_mfma_f32_32x32x16_bf16 v[50:65], v[248:251], v[226:229], v[50:65]
	ds_read_b128 v[248:251], v217 offset:4704
	v_sub_f32_e32 v74, v74, v223
	v_sub_f32_e32 v75, v75, v223
	v_sub_f32_e32 v76, v76, v223
	v_sub_f32_e32 v77, v77, v223
	v_exp_f32_e32 v74, v74
	v_exp_f32_e32 v75, v75
	s_waitcnt lgkmcnt(4)
	v_mfma_f32_32x32x16_bf16 v[34:49], v[210:213], v[226:229], v[34:49]
	ds_read_b128 v[210:213], v217 offset:9312
	v_exp_f32_e32 v76, v76
	v_exp_f32_e32 v77, v77
	v_sub_f32_e32 v78, v78, v223
	v_sub_f32_e32 v79, v79, v223
	v_sub_f32_e32 v80, v80, v223
	v_sub_f32_e32 v81, v81, v223
	s_waitcnt lgkmcnt(4)
	v_mfma_f32_32x32x16_bf16 v[18:33], v[236:239], v[226:229], v[18:33]
	ds_read_b128 v[236:239], v217 offset:13920
	v_exp_f32_e32 v78, v78
	v_exp_f32_e32 v79, v79
	v_exp_f32_e32 v80, v80
	v_exp_f32_e32 v81, v81
	v_add_f32_e32 v186, v66, v186
	v_add_f32_e32 v186, v67, v186
	s_waitcnt lgkmcnt(4)
	v_mfma_f32_32x32x16_bf16 v[2:17], v[240:243], v[226:229], v[2:17]
	v_add_f32_e32 v186, v68, v186
	v_add_f32_e32 v186, v69, v186
	v_add_f32_e32 v186, v70, v186
	v_add_f32_e32 v186, v71, v186
	v_add_f32_e32 v186, v72, v186
	v_add_f32_e32 v186, v73, v186
	v_cvt_pk_bf16_f32 v226, v74, v75
	v_cvt_pk_bf16_f32 v227, v76, v77
	v_cvt_pk_bf16_f32 v228, v78, v79
	v_cvt_pk_bf16_f32 v229, v80, v81
	s_nop 1
	s_waitcnt lgkmcnt(3)
	v_mfma_f32_32x32x16_bf16 v[50:65], v[244:247], v[226:229], v[50:65]
	v_add_f32_e32 v186, v74, v186
	v_add_f32_e32 v186, v75, v186
	s_waitcnt lgkmcnt(2)
	v_mfma_f32_32x32x16_bf16 v[34:49], v[248:251], v[226:229], v[34:49]
	v_add_f32_e32 v186, v76, v186
	v_add_f32_e32 v186, v77, v186
	s_waitcnt lgkmcnt(1)
	v_mfma_f32_32x32x16_bf16 v[18:33], v[210:213], v[226:229], v[18:33]
	v_add_f32_e32 v186, v78, v186
	v_add_f32_e32 v186, v79, v186
	s_waitcnt lgkmcnt(0)
	v_mfma_f32_32x32x16_bf16 v[2:17], v[236:239], v[226:229], v[2:17]
	v_add_f32_e32 v186, v80, v186
	v_add_f32_e32 v186, v81, v186
	v_add_f32_e32 v224, v225, v186
	s_add_i32 s13, s11, -4
	s_cmp_ge_u32 s13, s5
	s_cbranch_scc1 .LBB0_40
	s_barrier
	s_add_i32 s13, s11, -1
	s_cmp_ge_u32 s13, s5
	s_cbranch_scc1 .Latt2_wt_13
	s_waitcnt vmcnt(9)
	ds_write_b128 v219, v[102:105] offset:44032
	s_waitcnt vmcnt(8)
	ds_write_b128 v220, v[106:109] offset:44032
	s_waitcnt vmcnt(7)
	ds_write_b128 v221, v[114:117] offset:44032
	s_waitcnt vmcnt(6)
	ds_write_b128 v201, v[98:101]
	s_waitcnt vmcnt(5)
	ds_write_b128 v201, v[110:113] offset:9216
	v_add_co_u32_e32 v186, vcc, 0xffff6000, v206
	s_nop 1
	v_addc_co_u32_e32 v187, vcc, -1, v207, vcc
	global_load_dwordx4 v[102:105], v[186:187], off
	v_add_co_u32_e32 v186, vcc, 0xffff8000, v206
	s_nop 1
	v_addc_co_u32_e32 v187, vcc, -1, v207, vcc
	global_load_dwordx4 v[106:109], v[186:187], off
	v_add_co_u32_e32 v186, vcc, 0xffffa000, v206
	s_nop 1
	v_addc_co_u32_e32 v187, vcc, -1, v207, vcc
	global_load_dwordx4 v[114:117], v[186:187], off
	global_load_dwordx4 v[98:101], v[204:205], off offset:384
	global_load_dwordx4 v[110:113], v[208:209], off offset:384
	s_branch .Latt2_wd_14

.Latt2_wd_14:
	ds_read_b128 v[226:229], v215
	ds_read_b128 v[236:239], v215 offset:12800
	ds_read_b128 v[240:243], v215 offset:32
	ds_read_b128 v[244:247], v215 offset:12832
	ds_read_b128 v[248:251], v215 offset:64
	ds_read_b128 v[210:213], v215 offset:12864
	s_waitcnt lgkmcnt(5)
	v_mfma_f32_32x32x16_bf16 v[82:97], v[226:229], v[126:129], 0
	ds_read_b128 v[226:229], v215 offset:96
	s_waitcnt lgkmcnt(5)
	v_mfma_f32_32x32x16_bf16 v[66:81], v[236:239], v[126:129], 0
	ds_read_b128 v[236:239], v215 offset:12896
	s_waitcnt lgkmcnt(5)
	v_mfma_f32_32x32x16_bf16 v[82:97], v[240:243], v[142:145], v[82:97]
	ds_read_b128 v[240:243], v215 offset:128
	s_waitcnt lgkmcnt(5)
	v_mfma_f32_32x32x16_bf16 v[66:81], v[244:247], v[142:145], v[66:81]
	ds_read_b128 v[244:247], v215 offset:12928
	s_waitcnt lgkmcnt(5)
	v_mfma_f32_32x32x16_bf16 v[82:97], v[248:251], v[146:149], v[82:97]
	ds_read_b128 v[248:251], v215 offset:160
	s_waitcnt lgkmcnt(5)
	v_mfma_f32_32x32x16_bf16 v[66:81], v[210:213], v[146:149], v[66:81]
	ds_read_b128 v[210:213], v215 offset:12960
	s_waitcnt lgkmcnt(5)
	v_mfma_f32_32x32x16_bf16 v[82:97], v[226:229], v[150:153], v[82:97]
	ds_read_b128 v[226:229], v215 offset:192
	s_waitcnt lgkmcnt(5)
	v_mfma_f32_32x32x16_bf16 v[66:81], v[236:239], v[150:153], v[66:81]
	ds_read_b128 v[236:239], v215 offset:12992
	s_waitcnt lgkmcnt(5)
	v_mfma_f32_32x32x16_bf16 v[82:97], v[240:243], v[154:157], v[82:97]
	ds_read_b128 v[240:243], v215 offset:224
	s_waitcnt lgkmcnt(5)
	v_mfma_f32_32x32x16_bf16 v[66:81], v[244:247], v[154:157], v[66:81]
	ds_read_b128 v[244:247], v215 offset:13024
	s_waitcnt lgkmcnt(5)
	v_mfma_f32_32x32x16_bf16 v[82:97], v[248:251], v[158:161], v[82:97]
	ds_read_b128 v[248:251], v215 offset:256
	s_waitcnt lgkmcnt(5)
	v_mfma_f32_32x32x16_bf16 v[66:81], v[210:213], v[158:161], v[66:81]
	ds_read_b128 v[210:213], v215 offset:13056
	s_waitcnt lgkmcnt(5)
	v_mfma_f32_32x32x16_bf16 v[82:97], v[226:229], v[162:165], v[82:97]
	ds_read_b128 v[226:229], v215 offset:288
	s_waitcnt lgkmcnt(5)
	v_mfma_f32_32x32x16_bf16 v[66:81], v[236:239], v[162:165], v[66:81]
	ds_read_b128 v[236:239], v215 offset:13088
	s_waitcnt lgkmcnt(5)
	v_mfma_f32_32x32x16_bf16 v[82:97], v[240:243], v[166:169], v[82:97]
	ds_read_b128 v[240:243], v215 offset:320
	s_waitcnt lgkmcnt(5)
	v_mfma_f32_32x32x16_bf16 v[66:81], v[244:247], v[166:169], v[66:81]
	ds_read_b128 v[244:247], v215 offset:13120
	s_waitcnt lgkmcnt(5)
	v_mfma_f32_32x32x16_bf16 v[82:97], v[248:251], v[170:173], v[82:97]
	ds_read_b128 v[248:251], v215 offset:352
	s_waitcnt lgkmcnt(5)
	v_mfma_f32_32x32x16_bf16 v[66:81], v[210:213], v[170:173], v[66:81]
	ds_read_b128 v[210:213], v215 offset:13152
	s_waitcnt lgkmcnt(5)
	v_mfma_f32_32x32x16_bf16 v[82:97], v[226:229], v[174:177], v[82:97]
	s_waitcnt lgkmcnt(4)
	v_mfma_f32_32x32x16_bf16 v[66:81], v[236:239], v[174:177], v[66:81]
	s_waitcnt lgkmcnt(3)
	v_mfma_f32_32x32x16_bf16 v[82:97], v[240:243], v[178:181], v[82:97]
	s_waitcnt lgkmcnt(2)
	v_mfma_f32_32x32x16_bf16 v[66:81], v[244:247], v[178:181], v[66:81]
	s_waitcnt lgkmcnt(1)
	v_mfma_f32_32x32x16_bf16 v[82:97], v[248:251], v[182:185], v[82:97]
	s_waitcnt lgkmcnt(0)
	s_barrier
	v_mfma_f32_32x32x16_bf16 v[66:81], v[210:213], v[182:185], v[66:81]
	s_branch .Latt2_B_loop

.LBB0_283:
	s_andn2_b64 vcc, exec, s[0:1]
	s_cbranch_vccnz .LBB0_292
	s_mov_b32 s1, s35
	s_mov_b32 s0, s35
	s_mov_b32 s4, s98
	s_mov_b32 s5, -1
	v_mbcnt_lo_u32_b32 v0, -1, 0
	s_nop 0
	v_mbcnt_hi_u32_b32 v0, s5, v0
	v_lshl_add_u32 v0, s4, 6, v0
	v_readlane_b32 s4, v252, 0
	s_nop 0
	v_ashrrev_i32_e32 v2, 6, v0
	v_lshl_add_u32 v26, s4, 3, v2
	s_mov_b32 s4, 0xa000
	v_cmp_gt_i32_e32 vcc, s4, v26
	s_and_saveexec_b64 s[20:21], vcc
	s_cbranch_execz .LBB0_291
	v_and_b32_e32 v2, 63, v0
	v_lshlrev_b32_e32 v3, 3, v2
	v_xor_b32_e32 v4, 32, v2
	v_xor_b32_e32 v5, 16, v2
	v_xor_b32_e32 v6, 8, v2
	v_xor_b32_e32 v7, 4, v2
	v_xor_b32_e32 v8, 2, v2
	v_xor_b32_e32 v9, 1, v2
	v_lshlrev_b32_e32 v4, 2, v4
	v_lshlrev_b32_e32 v5, 2, v5
	v_lshlrev_b32_e32 v6, 2, v6
	v_lshlrev_b32_e32 v7, 2, v7
	v_lshlrev_b32_e32 v8, 2, v8
	v_lshlrev_b32_e32 v9, 2, v9
	v_lshlrev_b32_e32 v2, 4, v2
	v_add_u32_e32 v170, 0x1000, v2
	v_add_u32_e32 v171, 0x2000, v2
	v_add_u32_e32 v172, 0x3000, v2
	v_readlane_b32 s36, v252, 0
	v_readlane_b32 s64, v254, 19
	v_readlane_b32 s65, v254, 20
	v_readlane_b32 s66, v254, 21
	v_readlane_b32 s67, v254, 22
	v_readlane_b32 s68, v252, 3
	v_readlane_b32 s69, v252, 4
	v_readlane_b32 s72, v252, 33
	v_readlane_b32 s73, v252, 34
	s_nop 3
	s_lshl_b32 s36, s36, 3
	s_add_i32 s36, s36, s98
	s_mov_b32 s37, s99
	s_add_i32 s0, s36, 0xffffe000
	s_cmp_lt_u32 s36, 0x2000
	s_cselect_b32 s4, s36, s0
	s_cselect_b32 s6, s64, s66
	s_cselect_b32 s7, s65, s67
	s_mov_b32 s5, 0
	s_lshl_b64 s[4:5], s[4:5], 13
	s_add_u32 s38, s6, s4
	s_addc_u32 s39, s7, s5
	global_load_dwordx4 v[10:13], v2, s[38:39]
	global_load_dwordx4 v[14:17], v2, s[38:39] offset:1024
	global_load_dwordx4 v[18:21], v2, s[38:39] offset:2048
	global_load_dwordx4 v[22:25], v2, s[38:39] offset:3072
	global_load_dwordx4 v[26:29], v170, s[38:39]
	global_load_dwordx4 v[30:33], v170, s[38:39] offset:1024
	global_load_dwordx4 v[34:37], v170, s[38:39] offset:2048
	global_load_dwordx4 v[38:41], v170, s[38:39] offset:3072
.Lp1_loop:
	s_add_i32 s0, s36, 0xffffe000
	s_lshr_b32 s0, s0, 12
	s_cmp_lt_u32 s36, 0x2000
	s_cselect_b32 s0, 8, s0
	s_mul_i32 s0, s0, 0x6000
	s_add_u32 s74, s68, s0
	s_addc_u32 s75, s69, 0
	global_load_dwordx4 v[74:77], v2, s[72:73]
	global_load_dwordx4 v[106:109], v171, s[74:75]
	global_load_dwordx4 v[138:141], v2, s[74:75]
	global_load_dwordx4 v[78:81], v2, s[72:73] offset:1024
	global_load_dwordx4 v[110:113], v171, s[74:75] offset:1024
	global_load_dwordx4 v[142:145], v2, s[74:75] offset:1024
	global_load_dwordx4 v[82:85], v2, s[72:73] offset:2048
	global_load_dwordx4 v[114:117], v171, s[74:75] offset:2048
	global_load_dwordx4 v[146:149], v2, s[74:75] offset:2048
	global_load_dwordx4 v[86:89], v2, s[72:73] offset:3072
	global_load_dwordx4 v[118:121], v171, s[74:75] offset:3072
	global_load_dwordx4 v[150:153], v2, s[74:75] offset:3072
	global_load_dwordx4 v[90:93], v170, s[72:73]
	global_load_dwordx4 v[122:125], v172, s[74:75]
	global_load_dwordx4 v[154:157], v170, s[74:75]
	global_load_dwordx4 v[94:97], v170, s[72:73] offset:1024
	global_load_dwordx4 v[126:129], v172, s[74:75] offset:1024
	global_load_dwordx4 v[158:161], v170, s[74:75] offset:1024
	global_load_dwordx4 v[98:101], v170, s[72:73] offset:2048
	global_load_dwordx4 v[130:133], v172, s[74:75] offset:2048
	global_load_dwordx4 v[162:165], v170, s[74:75] offset:2048
	global_load_dwordx4 v[102:105], v170, s[72:73] offset:3072
	global_load_dwordx4 v[134:137], v172, s[74:75] offset:3072
	global_load_dwordx4 v[166:169], v170, s[74:75] offset:3072
	s_lshl_b32 s0, s36, 12
	s_lshr_b32 s1, s36, 20
	s_add_u32 s78, s68, s0
	s_addc_u32 s79, s69, s1
	s_add_u32 s78, s78, 0x1899b600
	s_addc_u32 s79, s79, 0
	s_add_i32 s40, s36, s37
	s_cmp_lt_u32 s40, 0xa000
	s_cbranch_scc0 .Lp1_last_a
	s_add_i32 s0, s40, 0xffffe000
	s_cmp_lt_u32 s40, 0x2000
	s_cselect_b32 s4, s40, s0
	s_cselect_b32 s6, s64, s66
	s_cselect_b32 s7, s65, s67
	s_mov_b32 s5, 0
	s_lshl_b64 s[4:5], s[4:5], 13
	s_add_u32 s38, s6, s4
	s_addc_u32 s39, s7, s5
	global_load_dwordx4 v[42:45], v2, s[38:39]
	global_load_dwordx4 v[46:49], v2, s[38:39] offset:1024
	global_load_dwordx4 v[50:53], v2, s[38:39] offset:2048
	global_load_dwordx4 v[54:57], v2, s[38:39] offset:3072
	global_load_dwordx4 v[58:61], v170, s[38:39]
	global_load_dwordx4 v[62:65], v170, s[38:39] offset:1024
	global_load_dwordx4 v[66:69], v170, s[38:39] offset:2048
	global_load_dwordx4 v[70:73], v170, s[38:39] offset:3072
	s_waitcnt vmcnt(8)
	s_branch .Lp1_go_a

.Lp1_go_a:
	v_mul_f32_e32 v173, v10, v10
	v_mul_f32_e32 v174, v11, v11
	v_fmac_f32_e32 v173, v12, v12
	v_fmac_f32_e32 v174, v13, v13
	v_fmac_f32_e32 v173, v14, v14
	v_fmac_f32_e32 v174, v15, v15
	v_fmac_f32_e32 v173, v16, v16
	v_fmac_f32_e32 v174, v17, v17
	v_fmac_f32_e32 v173, v18, v18
	v_fmac_f32_e32 v174, v19, v19
	v_fmac_f32_e32 v173, v20, v20
	v_fmac_f32_e32 v174, v21, v21
	v_fmac_f32_e32 v173, v22, v22
	v_fmac_f32_e32 v174, v23, v23
	v_fmac_f32_e32 v173, v24, v24
	v_fmac_f32_e32 v174, v25, v25
	v_fmac_f32_e32 v173, v26, v26
	v_fmac_f32_e32 v174, v27, v27
	v_fmac_f32_e32 v173, v28, v28
	v_fmac_f32_e32 v174, v29, v29
	v_fmac_f32_e32 v173, v30, v30
	v_fmac_f32_e32 v174, v31, v31
	v_fmac_f32_e32 v173, v32, v32
	v_fmac_f32_e32 v174, v33, v33
	v_fmac_f32_e32 v173, v34, v34
	v_fmac_f32_e32 v174, v35, v35
	v_fmac_f32_e32 v173, v36, v36
	v_fmac_f32_e32 v174, v37, v37
	v_fmac_f32_e32 v173, v38, v38
	v_fmac_f32_e32 v174, v39, v39
	v_fmac_f32_e32 v173, v40, v40
	v_fmac_f32_e32 v174, v41, v41
	v_add_f32_e32 v173, v173, v174
	ds_bpermute_b32 v174, v4, v173
	s_waitcnt lgkmcnt(0)
	v_add_f32_e32 v173, v173, v174
	ds_bpermute_b32 v174, v5, v173
	s_waitcnt lgkmcnt(0)
	v_add_f32_e32 v173, v173, v174
	ds_bpermute_b32 v174, v6, v173
	s_waitcnt lgkmcnt(0)
	v_add_f32_e32 v173, v173, v174
	ds_bpermute_b32 v174, v7, v173
	s_waitcnt lgkmcnt(0)
	v_add_f32_e32 v173, v173, v174
	ds_bpermute_b32 v174, v8, v173
	s_waitcnt lgkmcnt(0)
	v_add_f32_e32 v173, v173, v174
	ds_bpermute_b32 v174, v9, v173
	s_waitcnt lgkmcnt(0)
	v_add_f32_e32 v173, v173, v174
	v_fmamk_f32 v0, v173, 0x3a000000, v230
	v_rsq_f32_e32 v0, v0
	s_nop 0
	v_pk_mul_f32 v[10:11], v[10:11], v[0:1] op_sel_hi:[1,0]
	v_pk_mul_f32 v[12:13], v[12:13], v[0:1] op_sel_hi:[1,0]
	v_pk_mul_f32 v[10:11], v[74:75], v[10:11]
	v_pk_mul_f32 v[12:13], v[76:77], v[12:13]
	v_pk_add_f32 v[106:107], v[106:107], 1.0 op_sel_hi:[1,0]
	v_pk_add_f32 v[108:109], v[108:109], 1.0 op_sel_hi:[1,0]
	v_pk_fma_f32 v[10:11], v[106:107], v[10:11], v[138:139]
	v_pk_fma_f32 v[12:13], v[108:109], v[12:13], v[140:141]
	v_cvt_pk_bf16_f32 v10, v10, v11
	v_cvt_pk_bf16_f32 v11, v12, v13
	global_store_dwordx2 v3, v[10:11], s[78:79]
	v_pk_mul_f32 v[14:15], v[14:15], v[0:1] op_sel_hi:[1,0]
	v_pk_mul_f32 v[16:17], v[16:17], v[0:1] op_sel_hi:[1,0]
	v_pk_mul_f32 v[14:15], v[78:79], v[14:15]
	v_pk_mul_f32 v[16:17], v[80:81], v[16:17]
	v_pk_add_f32 v[110:111], v[110:111], 1.0 op_sel_hi:[1,0]
	v_pk_add_f32 v[112:113], v[112:113], 1.0 op_sel_hi:[1,0]
	v_pk_fma_f32 v[14:15], v[110:111], v[14:15], v[142:143]
	v_pk_fma_f32 v[16:17], v[112:113], v[16:17], v[144:145]
	v_cvt_pk_bf16_f32 v14, v14, v15
	v_cvt_pk_bf16_f32 v15, v16, v17
	global_store_dwordx2 v3, v[14:15], s[78:79] offset:512
	v_pk_mul_f32 v[18:19], v[18:19], v[0:1] op_sel_hi:[1,0]
	v_pk_mul_f32 v[20:21], v[20:21], v[0:1] op_sel_hi:[1,0]
	v_pk_mul_f32 v[18:19], v[82:83], v[18:19]
	v_pk_mul_f32 v[20:21], v[84:85], v[20:21]
	v_pk_add_f32 v[114:115], v[114:115], 1.0 op_sel_hi:[1,0]
	v_pk_add_f32 v[116:117], v[116:117], 1.0 op_sel_hi:[1,0]
	v_pk_fma_f32 v[18:19], v[114:115], v[18:19], v[146:147]
	v_pk_fma_f32 v[20:21], v[116:117], v[20:21], v[148:149]
	v_cvt_pk_bf16_f32 v18, v18, v19
	v_cvt_pk_bf16_f32 v19, v20, v21
	global_store_dwordx2 v3, v[18:19], s[78:79] offset:1024
	v_pk_mul_f32 v[22:23], v[22:23], v[0:1] op_sel_hi:[1,0]
	v_pk_mul_f32 v[24:25], v[24:25], v[0:1] op_sel_hi:[1,0]
	v_pk_mul_f32 v[22:23], v[86:87], v[22:23]
	v_pk_mul_f32 v[24:25], v[88:89], v[24:25]
	v_pk_add_f32 v[118:119], v[118:119], 1.0 op_sel_hi:[1,0]
	v_pk_add_f32 v[120:121], v[120:121], 1.0 op_sel_hi:[1,0]
	v_pk_fma_f32 v[22:23], v[118:119], v[22:23], v[150:151]
	v_pk_fma_f32 v[24:25], v[120:121], v[24:25], v[152:153]
	v_cvt_pk_bf16_f32 v22, v22, v23
	v_cvt_pk_bf16_f32 v23, v24, v25
	global_store_dwordx2 v3, v[22:23], s[78:79] offset:1536
	v_pk_mul_f32 v[26:27], v[26:27], v[0:1] op_sel_hi:[1,0]
	v_pk_mul_f32 v[28:29], v[28:29], v[0:1] op_sel_hi:[1,0]
	v_pk_mul_f32 v[26:27], v[90:91], v[26:27]
	v_pk_mul_f32 v[28:29], v[92:93], v[28:29]
	v_pk_add_f32 v[122:123], v[122:123], 1.0 op_sel_hi:[1,0]
	v_pk_add_f32 v[124:125], v[124:125], 1.0 op_sel_hi:[1,0]
	v_pk_fma_f32 v[26:27], v[122:123], v[26:27], v[154:155]
	v_pk_fma_f32 v[28:29], v[124:125], v[28:29], v[156:157]
	v_cvt_pk_bf16_f32 v26, v26, v27
	v_cvt_pk_bf16_f32 v27, v28, v29
	global_store_dwordx2 v3, v[26:27], s[78:79] offset:2048
	v_pk_mul_f32 v[30:31], v[30:31], v[0:1] op_sel_hi:[1,0]
	v_pk_mul_f32 v[32:33], v[32:33], v[0:1] op_sel_hi:[1,0]
	v_pk_mul_f32 v[30:31], v[94:95], v[30:31]
	v_pk_mul_f32 v[32:33], v[96:97], v[32:33]
	v_pk_add_f32 v[126:127], v[126:127], 1.0 op_sel_hi:[1,0]
	v_pk_add_f32 v[128:129], v[128:129], 1.0 op_sel_hi:[1,0]
	v_pk_fma_f32 v[30:31], v[126:127], v[30:31], v[158:159]
	v_pk_fma_f32 v[32:33], v[128:129], v[32:33], v[160:161]
	v_cvt_pk_bf16_f32 v30, v30, v31
	v_cvt_pk_bf16_f32 v31, v32, v33
	global_store_dwordx2 v3, v[30:31], s[78:79] offset:2560
	v_pk_mul_f32 v[34:35], v[34:35], v[0:1] op_sel_hi:[1,0]
	v_pk_mul_f32 v[36:37], v[36:37], v[0:1] op_sel_hi:[1,0]
	v_pk_mul_f32 v[34:35], v[98:99], v[34:35]
	v_pk_mul_f32 v[36:37], v[100:101], v[36:37]
	v_pk_add_f32 v[130:131], v[130:131], 1.0 op_sel_hi:[1,0]
	v_pk_add_f32 v[132:133], v[132:133], 1.0 op_sel_hi:[1,0]
	v_pk_fma_f32 v[34:35], v[130:131], v[34:35], v[162:163]
	v_pk_fma_f32 v[36:37], v[132:133], v[36:37], v[164:165]
	v_cvt_pk_bf16_f32 v34, v34, v35
	v_cvt_pk_bf16_f32 v35, v36, v37
	global_store_dwordx2 v3, v[34:35], s[78:79] offset:3072
	v_pk_mul_f32 v[38:39], v[38:39], v[0:1] op_sel_hi:[1,0]
	v_pk_mul_f32 v[40:41], v[40:41], v[0:1] op_sel_hi:[1,0]
	v_pk_mul_f32 v[38:39], v[102:103], v[38:39]
	v_pk_mul_f32 v[40:41], v[104:105], v[40:41]
	v_pk_add_f32 v[134:135], v[134:135], 1.0 op_sel_hi:[1,0]
	v_pk_add_f32 v[136:137], v[136:137], 1.0 op_sel_hi:[1,0]
	v_pk_fma_f32 v[38:39], v[134:135], v[38:39], v[166:167]
	v_pk_fma_f32 v[40:41], v[136:137], v[40:41], v[168:169]
	v_cvt_pk_bf16_f32 v38, v38, v39
	v_cvt_pk_bf16_f32 v39, v40, v41
	global_store_dwordx2 v3, v[38:39], s[78:79] offset:3584
	s_mov_b32 s36, s40
	s_cmp_lt_u32 s36, 0xa000
	s_cbranch_scc0 .Lp1_done
	s_add_i32 s0, s36, 0xffffe000
	s_lshr_b32 s0, s0, 12
	s_cmp_lt_u32 s36, 0x2000
	s_cselect_b32 s0, 8, s0
	s_mul_i32 s0, s0, 0x6000
	s_add_u32 s74, s68, s0
	s_addc_u32 s75, s69, 0
	global_load_dwordx4 v[74:77], v2, s[72:73]
	global_load_dwordx4 v[106:109], v171, s[74:75]
	global_load_dwordx4 v[138:141], v2, s[74:75]
	global_load_dwordx4 v[78:81], v2, s[72:73] offset:1024
	global_load_dwordx4 v[110:113], v171, s[74:75] offset:1024
	global_load_dwordx4 v[142:145], v2, s[74:75] offset:1024
	global_load_dwordx4 v[82:85], v2, s[72:73] offset:2048
	global_load_dwordx4 v[114:117], v171, s[74:75] offset:2048
	global_load_dwordx4 v[146:149], v2, s[74:75] offset:2048
	global_load_dwordx4 v[86:89], v2, s[72:73] offset:3072
	global_load_dwordx4 v[118:121], v171, s[74:75] offset:3072
	global_load_dwordx4 v[150:153], v2, s[74:75] offset:3072
	global_load_dwordx4 v[90:93], v170, s[72:73]
	global_load_dwordx4 v[122:125], v172, s[74:75]
	global_load_dwordx4 v[154:157], v170, s[74:75]
	global_load_dwordx4 v[94:97], v170, s[72:73] offset:1024
	global_load_dwordx4 v[126:129], v172, s[74:75] offset:1024
	global_load_dwordx4 v[158:161], v170, s[74:75] offset:1024
	global_load_dwordx4 v[98:101], v170, s[72:73] offset:2048
	global_load_dwordx4 v[130:133], v172, s[74:75] offset:2048
	global_load_dwordx4 v[162:165], v170, s[74:75] offset:2048
	global_load_dwordx4 v[102:105], v170, s[72:73] offset:3072
	global_load_dwordx4 v[134:137], v172, s[74:75] offset:3072
	global_load_dwordx4 v[166:169], v170, s[74:75] offset:3072
	s_lshl_b32 s0, s36, 12
	s_lshr_b32 s1, s36, 20
	s_add_u32 s78, s68, s0
	s_addc_u32 s79, s69, s1
	s_add_u32 s78, s78, 0x1899b600
	s_addc_u32 s79, s79, 0
	s_add_i32 s40, s36, s37
	s_cmp_lt_u32 s40, 0xa000
	s_cbranch_scc0 .Lp1_last_b
	s_add_i32 s0, s40, 0xffffe000
	s_cmp_lt_u32 s40, 0x2000
	s_cselect_b32 s4, s40, s0
	s_cselect_b32 s6, s64, s66
	s_cselect_b32 s7, s65, s67
	s_mov_b32 s5, 0
	s_lshl_b64 s[4:5], s[4:5], 13
	s_add_u32 s38, s6, s4
	s_addc_u32 s39, s7, s5
	global_load_dwordx4 v[10:13], v2, s[38:39]
	global_load_dwordx4 v[14:17], v2, s[38:39] offset:1024
	global_load_dwordx4 v[18:21], v2, s[38:39] offset:2048
	global_load_dwordx4 v[22:25], v2, s[38:39] offset:3072
	global_load_dwordx4 v[26:29], v170, s[38:39]
	global_load_dwordx4 v[30:33], v170, s[38:39] offset:1024
	global_load_dwordx4 v[34:37], v170, s[38:39] offset:2048
	global_load_dwordx4 v[38:41], v170, s[38:39] offset:3072
	s_waitcnt vmcnt(8)
	s_branch .Lp1_go_b

.Lp1_go_b:
	v_mul_f32_e32 v173, v42, v42
	v_mul_f32_e32 v174, v43, v43
	v_fmac_f32_e32 v173, v44, v44
	v_fmac_f32_e32 v174, v45, v45
	v_fmac_f32_e32 v173, v46, v46
	v_fmac_f32_e32 v174, v47, v47
	v_fmac_f32_e32 v173, v48, v48
	v_fmac_f32_e32 v174, v49, v49
	v_fmac_f32_e32 v173, v50, v50
	v_fmac_f32_e32 v174, v51, v51
	v_fmac_f32_e32 v173, v52, v52
	v_fmac_f32_e32 v174, v53, v53
	v_fmac_f32_e32 v173, v54, v54
	v_fmac_f32_e32 v174, v55, v55
	v_fmac_f32_e32 v173, v56, v56
	v_fmac_f32_e32 v174, v57, v57
	v_fmac_f32_e32 v173, v58, v58
	v_fmac_f32_e32 v174, v59, v59
	v_fmac_f32_e32 v173, v60, v60
	v_fmac_f32_e32 v174, v61, v61
	v_fmac_f32_e32 v173, v62, v62
	v_fmac_f32_e32 v174, v63, v63
	v_fmac_f32_e32 v173, v64, v64
	v_fmac_f32_e32 v174, v65, v65
	v_fmac_f32_e32 v173, v66, v66
	v_fmac_f32_e32 v174, v67, v67
	v_fmac_f32_e32 v173, v68, v68
	v_fmac_f32_e32 v174, v69, v69
	v_fmac_f32_e32 v173, v70, v70
	v_fmac_f32_e32 v174, v71, v71
	v_fmac_f32_e32 v173, v72, v72
	v_fmac_f32_e32 v174, v73, v73
	v_add_f32_e32 v173, v173, v174
	ds_bpermute_b32 v174, v4, v173
	s_waitcnt lgkmcnt(0)
	v_add_f32_e32 v173, v173, v174
	ds_bpermute_b32 v174, v5, v173
	s_waitcnt lgkmcnt(0)
	v_add_f32_e32 v173, v173, v174
	ds_bpermute_b32 v174, v6, v173
	s_waitcnt lgkmcnt(0)
	v_add_f32_e32 v173, v173, v174
	ds_bpermute_b32 v174, v7, v173
	s_waitcnt lgkmcnt(0)
	v_add_f32_e32 v173, v173, v174
	ds_bpermute_b32 v174, v8, v173
	s_waitcnt lgkmcnt(0)
	v_add_f32_e32 v173, v173, v174
	ds_bpermute_b32 v174, v9, v173
	s_waitcnt lgkmcnt(0)
	v_add_f32_e32 v173, v173, v174
	v_fmamk_f32 v0, v173, 0x3a000000, v230
	v_rsq_f32_e32 v0, v0
	s_nop 0
	v_pk_mul_f32 v[42:43], v[42:43], v[0:1] op_sel_hi:[1,0]
	v_pk_mul_f32 v[44:45], v[44:45], v[0:1] op_sel_hi:[1,0]
	v_pk_mul_f32 v[42:43], v[74:75], v[42:43]
	v_pk_mul_f32 v[44:45], v[76:77], v[44:45]
	v_pk_add_f32 v[106:107], v[106:107], 1.0 op_sel_hi:[1,0]
	v_pk_add_f32 v[108:109], v[108:109], 1.0 op_sel_hi:[1,0]
	v_pk_fma_f32 v[42:43], v[106:107], v[42:43], v[138:139]
	v_pk_fma_f32 v[44:45], v[108:109], v[44:45], v[140:141]
	v_cvt_pk_bf16_f32 v42, v42, v43
	v_cvt_pk_bf16_f32 v43, v44, v45
	global_store_dwordx2 v3, v[42:43], s[78:79]
	v_pk_mul_f32 v[46:47], v[46:47], v[0:1] op_sel_hi:[1,0]
	v_pk_mul_f32 v[48:49], v[48:49], v[0:1] op_sel_hi:[1,0]
	v_pk_mul_f32 v[46:47], v[78:79], v[46:47]
	v_pk_mul_f32 v[48:49], v[80:81], v[48:49]
	v_pk_add_f32 v[110:111], v[110:111], 1.0 op_sel_hi:[1,0]
	v_pk_add_f32 v[112:113], v[112:113], 1.0 op_sel_hi:[1,0]
	v_pk_fma_f32 v[46:47], v[110:111], v[46:47], v[142:143]
	v_pk_fma_f32 v[48:49], v[112:113], v[48:49], v[144:145]
	v_cvt_pk_bf16_f32 v46, v46, v47
	v_cvt_pk_bf16_f32 v47, v48, v49
	global_store_dwordx2 v3, v[46:47], s[78:79] offset:512
	v_pk_mul_f32 v[50:51], v[50:51], v[0:1] op_sel_hi:[1,0]
	v_pk_mul_f32 v[52:53], v[52:53], v[0:1] op_sel_hi:[1,0]
	v_pk_mul_f32 v[50:51], v[82:83], v[50:51]
	v_pk_mul_f32 v[52:53], v[84:85], v[52:53]
	v_pk_add_f32 v[114:115], v[114:115], 1.0 op_sel_hi:[1,0]
	v_pk_add_f32 v[116:117], v[116:117], 1.0 op_sel_hi:[1,0]
	v_pk_fma_f32 v[50:51], v[114:115], v[50:51], v[146:147]
	v_pk_fma_f32 v[52:53], v[116:117], v[52:53], v[148:149]
	v_cvt_pk_bf16_f32 v50, v50, v51
	v_cvt_pk_bf16_f32 v51, v52, v53
	global_store_dwordx2 v3, v[50:51], s[78:79] offset:1024
	v_pk_mul_f32 v[54:55], v[54:55], v[0:1] op_sel_hi:[1,0]
	v_pk_mul_f32 v[56:57], v[56:57], v[0:1] op_sel_hi:[1,0]
	v_pk_mul_f32 v[54:55], v[86:87], v[54:55]
	v_pk_mul_f32 v[56:57], v[88:89], v[56:57]
	v_pk_add_f32 v[118:119], v[118:119], 1.0 op_sel_hi:[1,0]
	v_pk_add_f32 v[120:121], v[120:121], 1.0 op_sel_hi:[1,0]
	v_pk_fma_f32 v[54:55], v[118:119], v[54:55], v[150:151]
	v_pk_fma_f32 v[56:57], v[120:121], v[56:57], v[152:153]
	v_cvt_pk_bf16_f32 v54, v54, v55
	v_cvt_pk_bf16_f32 v55, v56, v57
	global_store_dwordx2 v3, v[54:55], s[78:79] offset:1536
	v_pk_mul_f32 v[58:59], v[58:59], v[0:1] op_sel_hi:[1,0]
	v_pk_mul_f32 v[60:61], v[60:61], v[0:1] op_sel_hi:[1,0]
	v_pk_mul_f32 v[58:59], v[90:91], v[58:59]
	v_pk_mul_f32 v[60:61], v[92:93], v[60:61]
	v_pk_add_f32 v[122:123], v[122:123], 1.0 op_sel_hi:[1,0]
	v_pk_add_f32 v[124:125], v[124:125], 1.0 op_sel_hi:[1,0]
	v_pk_fma_f32 v[58:59], v[122:123], v[58:59], v[154:155]
	v_pk_fma_f32 v[60:61], v[124:125], v[60:61], v[156:157]
	v_cvt_pk_bf16_f32 v58, v58, v59
	v_cvt_pk_bf16_f32 v59, v60, v61
	global_store_dwordx2 v3, v[58:59], s[78:79] offset:2048
	v_pk_mul_f32 v[62:63], v[62:63], v[0:1] op_sel_hi:[1,0]
	v_pk_mul_f32 v[64:65], v[64:65], v[0:1] op_sel_hi:[1,0]
	v_pk_mul_f32 v[62:63], v[94:95], v[62:63]
	v_pk_mul_f32 v[64:65], v[96:97], v[64:65]
	v_pk_add_f32 v[126:127], v[126:127], 1.0 op_sel_hi:[1,0]
	v_pk_add_f32 v[128:129], v[128:129], 1.0 op_sel_hi:[1,0]
	v_pk_fma_f32 v[62:63], v[126:127], v[62:63], v[158:159]
	v_pk_fma_f32 v[64:65], v[128:129], v[64:65], v[160:161]
	v_cvt_pk_bf16_f32 v62, v62, v63
	v_cvt_pk_bf16_f32 v63, v64, v65
	global_store_dwordx2 v3, v[62:63], s[78:79] offset:2560
	v_pk_mul_f32 v[66:67], v[66:67], v[0:1] op_sel_hi:[1,0]
	v_pk_mul_f32 v[68:69], v[68:69], v[0:1] op_sel_hi:[1,0]
	v_pk_mul_f32 v[66:67], v[98:99], v[66:67]
	v_pk_mul_f32 v[68:69], v[100:101], v[68:69]
	v_pk_add_f32 v[130:131], v[130:131], 1.0 op_sel_hi:[1,0]
	v_pk_add_f32 v[132:133], v[132:133], 1.0 op_sel_hi:[1,0]
	v_pk_fma_f32 v[66:67], v[130:131], v[66:67], v[162:163]
	v_pk_fma_f32 v[68:69], v[132:133], v[68:69], v[164:165]
	v_cvt_pk_bf16_f32 v66, v66, v67
	v_cvt_pk_bf16_f32 v67, v68, v69
	global_store_dwordx2 v3, v[66:67], s[78:79] offset:3072
	v_pk_mul_f32 v[70:71], v[70:71], v[0:1] op_sel_hi:[1,0]
	v_pk_mul_f32 v[72:73], v[72:73], v[0:1] op_sel_hi:[1,0]
	v_pk_mul_f32 v[70:71], v[102:103], v[70:71]
	v_pk_mul_f32 v[72:73], v[104:105], v[72:73]
	v_pk_add_f32 v[134:135], v[134:135], 1.0 op_sel_hi:[1,0]
	v_pk_add_f32 v[136:137], v[136:137], 1.0 op_sel_hi:[1,0]
	v_pk_fma_f32 v[70:71], v[134:135], v[70:71], v[166:167]
	v_pk_fma_f32 v[72:73], v[136:137], v[72:73], v[168:169]
	v_cvt_pk_bf16_f32 v70, v70, v71
	v_cvt_pk_bf16_f32 v71, v72, v73
	global_store_dwordx2 v3, v[70:71], s[78:79] offset:3584
	s_mov_b32 s36, s40
	s_cmp_lt_u32 s36, 0xa000
	s_cbranch_scc1 .Lp1_loop
.Lp1_done:
	v_readlane_b32 s64, v254, 19
	v_readlane_b32 s65, v254, 20
	v_readlane_b32 s66, v254, 21
	v_readlane_b32 s67, v254, 22
	v_readlane_b32 s68, v254, 23
	v_readlane_b32 s69, v254, 24
	v_readlane_b32 s70, v254, 25
	v_readlane_b32 s71, v254, 26
	v_readlane_b32 s72, v254, 27
	v_readlane_b32 s73, v254, 28
	v_readlane_b32 s74, v254, 29
	v_readlane_b32 s75, v254, 30
	v_readlane_b32 s76, v254, 31
	v_readlane_b32 s77, v254, 32
	v_readlane_b32 s78, v254, 33
	v_readlane_b32 s79, v254, 34
